# GEMM tile prologues: vmcnt(0) between the first LDS-DMA loads relaxed to a counted wait (covers all older ops, no longer serializes the first loads' latency)
# baseline (speedup 1.0000x reference)
.LBB0_138:
	s_and_b64 vcc, exec, s[8:9]
	s_cbranch_vccz .LBB0_178
	v_mov_b32_e32 v140, v201
	s_lshl_b32 s39, s50, 8
	v_ashrrev_i32_e32 v0, 31, v140
	v_lshrrev_b32_e32 v0, 26, v0
	v_add_u32_e32 v0, v140, v0
	v_ashrrev_i32_e32 v14, 6, v0
	v_bfe_i32 v0, v140, 27, 1
	v_lshlrev_b32_e32 v2, 4, v140
	v_lshrrev_b32_e32 v0, 22, v0
	v_add_u32_e32 v0, v2, v0
	v_and_b32_e32 v0, 0xfffffc00, v0
	v_sub_u32_e32 v0, v2, v0
	v_lshrrev_b32_e32 v3, 4, v0
	v_bitop3_b32 v3, v3, v0, 32 bitop3:0x6c
	v_ashrrev_i32_e32 v0, 31, v0
	v_lshrrev_b32_e32 v0, 26, v0
	v_lshlrev_b32_e32 v4, 3, v14
	v_add_u32_e32 v0, v3, v0
	v_and_b32_e32 v4, 0xfffff0, v4
	v_ashrrev_i32_e32 v17, 6, v0
	v_add_u32_e32 v0, v17, v4
	v_lshlrev_b32_e32 v4, 5, v14
	v_and_b32_e32 v16, 32, v4
	v_mul_i32_i24_e32 v4, 64, v17
	v_sub_u32_e32 v3, v3, v4
	v_ashrrev_i16_sdwa v3, v217, sext(v3) dst_sel:DWORD dst_unused:UNUSED_PAD src0_sel:DWORD src1_sel:BYTE_0
	v_add_u32_e32 v2, 0x2000, v2
	v_bfe_i32 v18, v3, 0, 16
	v_ashrrev_i32_e32 v3, 31, v2
	v_lshrrev_b32_e32 v3, 22, v3
	v_add_u32_e32 v3, v2, v3
	v_ashrrev_i32_e32 v20, 10, v3
	v_mul_i32_i24_e32 v3, 0x400, v20
	v_sub_u32_e32 v2, v2, v3
	v_lshrrev_b32_e32 v3, 4, v2
	v_bitop3_b32 v2, v3, v2, 32 bitop3:0x6c
	v_ashrrev_i32_e32 v4, 31, v2
	v_lshrrev_b32_e32 v4, 26, v4
	v_add_u32_e32 v4, v2, v4
	v_ashrrev_i32_e32 v19, 6, v140
	v_lshlrev_b32_e32 v3, 3, v20
	v_ashrrev_i32_e32 v22, 6, v4
	v_and_b32_e32 v4, 0xc0, v4
	v_readfirstlane_b32 s8, v19
	v_and_b32_e32 v3, 0xfffff0, v3
	v_sub_u32_e32 v2, v2, v4
	s_lshl_b32 s33, s8, 10
	s_movk_i32 s8, 0xb00
	v_add_u32_e32 v3, v22, v3
	v_ashrrev_i16_sdwa v2, v217, sext(v2) dst_sel:DWORD dst_unused:UNUSED_PAD src0_sel:DWORD src1_sel:BYTE_0
	s_lshl_b32 s36, s56, 8
	s_mul_i32 s10, s56, 0x160000
	v_readlane_b32 s16, v255, 5
	v_mul_lo_u32 v0, v0, s8
	v_bfe_i32 v23, v2, 0, 16
	v_mul_lo_u32 v2, v3, s8
	s_mul_hi_i32 s11, s36, 0x1600
	s_add_u32 s8, s16, s10
	v_readlane_b32 s17, v255, 6
	v_lshlrev_b32_e32 v5, 5, v20
	s_addc_u32 s9, s17, s11
	s_add_i32 s37, s33, 0
	v_or_b32_e32 v0, v0, v16
	v_and_b32_e32 v21, 32, v5
	s_add_i32 s42, s37, 0x10000
	v_add_lshl_u32 v0, v0, v18, 1
	v_or_b32_e32 v2, v2, v21
	s_mov_b32 m0, s42
	s_add_i32 s43, s37, 0x12000
	v_add_lshl_u32 v130, v2, v23, 1
	global_load_lds_dwordx4 v0, s[8:9]
	v_mov_b32_e32 v131, v1
	s_mov_b32 m0, s43
	s_mul_i32 s12, s50, 0x160000
	v_readlane_b32 s14, v253, 58
	v_lshl_add_u64 v[2:3], s[8:9], 0, v[0:1]
	v_lshl_add_u64 v[4:5], s[8:9], 0, v[130:131]
	global_load_lds_dwordx4 v130, s[8:9]
	s_mul_hi_i32 s13, s39, 0x1600
	v_readlane_b32 s15, v253, 59
	s_add_u32 s8, s14, s12
	s_addc_u32 s9, s15, s13
	s_mov_b32 m0, s37
	s_add_i32 s54, s37, 0x2000
	global_load_lds_dwordx4 v0, s[8:9]
	s_mov_b32 m0, s54
	s_waitcnt vmcnt(3)
	v_lshl_add_u64 v[6:7], s[8:9], 0, v[0:1]
	v_lshl_add_u64 v[8:9], s[8:9], 0, v[130:131]
	global_load_lds_dwordx4 v130, s[8:9]
	s_or_b32 s8, s36, 0x80
	s_mul_hi_i32 s9, s8, 0x1600
	s_mulk_i32 s8, 0x1600
	s_add_u32 s8, s16, s8
	s_addc_u32 s9, s17, s9
	s_add_i32 s55, s37, 0x14000
	s_mov_b32 m0, s55
	s_add_i32 s57, s37, 0x16000
	global_load_lds_dwordx4 v0, s[8:9]
	s_mov_b32 m0, s57
	s_or_b32 s38, s39, 0x80
	v_lshl_add_u64 v[10:11], s[8:9], 0, v[0:1]
	v_lshl_add_u64 v[12:13], s[8:9], 0, v[130:131]
	global_load_lds_dwordx4 v130, s[8:9]
	s_mul_i32 s8, s38, 0x1600
	s_mul_hi_i32 s9, s38, 0x1600
	s_add_u32 s8, s14, s8
	s_addc_u32 s9, s15, s9
	s_add_i32 s60, s37, 0x4000
	s_mov_b32 m0, s60
	s_add_i32 s61, s37, 0x6000
	global_load_lds_dwordx4 v0, s[8:9]
	s_mov_b32 m0, s61
	v_ashrrev_i32_e32 v15, 8, v140
	global_load_lds_dwordx4 v130, s[8:9]
	v_cmp_eq_u32_e32 vcc, 1, v15
	s_and_saveexec_b64 s[14:15], vcc
	s_cbranch_execz .LBB0_141
	s_barrier

.LBB0_179:
	s_and_b64 vcc, exec, s[8:9]
	s_cbranch_vccz .LBB0_193
	v_mov_b32_e32 v142, v201
	s_lshl_b32 s38, s56, 9
	v_ashrrev_i32_e32 v0, 31, v142
	v_lshrrev_b32_e32 v0, 26, v0
	v_add_u32_e32 v0, v142, v0
	v_ashrrev_i32_e32 v16, 6, v0
	v_bfe_i32 v0, v142, 27, 1
	v_lshlrev_b32_e32 v2, 4, v142
	v_lshrrev_b32_e32 v0, 22, v0
	v_add_u32_e32 v0, v2, v0
	v_and_b32_e32 v0, 0xfffffc00, v0
	v_sub_u32_e32 v0, v2, v0
	v_lshrrev_b32_e32 v3, 4, v0
	v_bitop3_b32 v3, v3, v0, 32 bitop3:0x6c
	v_ashrrev_i32_e32 v0, 31, v0
	v_lshrrev_b32_e32 v0, 26, v0
	v_add_u32_e32 v0, v3, v0
	v_ashrrev_i32_e32 v18, 6, v0
	v_mul_i32_i24_e32 v5, 64, v18
	v_sub_u32_e32 v3, v3, v5
	v_lshlrev_b32_e32 v4, 3, v16
	v_lshlrev_b32_e32 v0, 5, v16
	v_ashrrev_i16_sdwa v3, v217, sext(v3) dst_sel:DWORD dst_unused:UNUSED_PAD src0_sel:DWORD src1_sel:BYTE_0
	v_and_b32_e32 v4, 0x1ffff0, v4
	v_and_b32_e32 v0, 32, v0
	v_bfe_i32 v19, v3, 0, 16
	v_add_u32_e32 v0, v0, v19
	v_add_lshl_u32 v3, v18, v4, 11
	v_add_u32_e32 v2, 0x2000, v2
	v_lshl_add_u32 v0, v0, 1, v3
	v_ashrrev_i32_e32 v3, 31, v2
	v_lshrrev_b32_e32 v3, 22, v3
	v_add_u32_e32 v3, v2, v3
	v_ashrrev_i32_e32 v21, 10, v3
	v_mul_i32_i24_e32 v3, 0x400, v21
	v_sub_u32_e32 v2, v2, v3
	v_lshrrev_b32_e32 v3, 4, v2
	v_bitop3_b32 v2, v3, v2, 32 bitop3:0x6c
	v_ashrrev_i32_e32 v4, 31, v2
	v_ashrrev_i32_e32 v20, 6, v142
	v_lshrrev_b32_e32 v4, 26, v4
	v_readfirstlane_b32 s8, v20
	v_add_u32_e32 v4, v2, v4
	s_ashr_i32 s39, s38, 31
	s_lshl_b32 s33, s8, 10
	v_ashrrev_i32_e32 v22, 6, v4
	v_and_b32_e32 v4, 0xc0, v4
	s_lshl_b32 s10, s50, 8
	s_lshl_b64 s[12:13], s[38:39], 11
	v_readlane_b32 s16, v254, 61
	v_sub_u32_e32 v2, v2, v4
	s_add_u32 s8, s16, s12
	v_readlane_b32 s17, v254, 62
	v_lshlrev_b32_e32 v3, 3, v21
	v_lshlrev_b32_e32 v5, 5, v21
	v_ashrrev_i16_sdwa v2, v217, sext(v2) dst_sel:DWORD dst_unused:UNUSED_PAD src0_sel:DWORD src1_sel:BYTE_0
	s_addc_u32 s9, s17, s13
	s_add_i32 s36, s33, 0
	v_and_b32_e32 v3, 0x1ffff0, v3
	v_and_b32_e32 v5, 32, v5
	v_bfe_i32 v23, v2, 0, 16
	s_add_i32 s37, s36, 0x10000
	s_ashr_i32 s11, s10, 31
	v_add_u32_e32 v2, v5, v23
	v_add_lshl_u32 v3, v22, v3, 11
	s_mov_b32 m0, s37
	s_add_i32 s39, s36, 0x12000
	s_lshl_b64 s[14:15], s[10:11], 11
	v_lshl_add_u32 v2, v2, 1, v3
	global_load_lds_dwordx4 v0, s[8:9]
	v_mov_b32_e32 v3, v1
	s_mov_b32 m0, s39
	s_add_u32 s54, s44, s14
	v_lshl_add_u64 v[4:5], s[8:9], 0, v[0:1]
	s_waitcnt vmcnt(1)
	v_lshl_add_u64 v[6:7], s[8:9], 0, v[2:3]
	global_load_lds_dwordx4 v2, s[8:9]
	s_addc_u32 s55, s45, s15
	s_or_b32 s8, s38, 0x80
	s_ashr_i32 s9, s8, 31
	s_add_i32 s70, s36, 0x2000
	s_lshl_b64 s[8:9], s[8:9], 11
	s_mov_b32 m0, s36
	s_add_u32 s8, s16, s8
	global_load_lds_dwordx4 v0, s[54:55]
	s_mov_b32 m0, s70
	s_addc_u32 s9, s17, s9
	s_add_i32 s71, s36, 0x14000
	global_load_lds_dwordx4 v2, s[54:55]
	s_mov_b32 m0, s71
	s_add_i32 s72, s36, 0x16000
	global_load_lds_dwordx4 v0, s[8:9]
	s_mov_b32 m0, s72
	v_lshl_add_u64 v[12:13], s[8:9], 0, v[0:1]
	v_lshl_add_u64 v[14:15], s[8:9], 0, v[2:3]
	global_load_lds_dwordx4 v2, s[8:9]
	s_or_b32 s8, s10, 0x80
	s_ashr_i32 s9, s8, 31
	s_lshl_b64 s[42:43], s[8:9], 11
	s_add_u32 s60, s44, s42
	s_addc_u32 s61, s45, s43
	s_add_i32 s73, s36, 0x4000
	s_mov_b32 m0, s73
	s_add_i32 s88, s36, 0x6000
	global_load_lds_dwordx4 v0, s[60:61]
	s_mov_b32 m0, s88
	v_ashrrev_i32_e32 v17, 8, v142
	global_load_lds_dwordx4 v2, s[60:61]
	v_lshl_add_u64 v[8:9], s[54:55], 0, v[0:1]
	v_lshl_add_u64 v[10:11], s[54:55], 0, v[2:3]
	v_cmp_eq_u32_e32 vcc, 1, v17
	s_and_saveexec_b64 s[42:43], vcc
	s_cbranch_execz .LBB0_182
	s_barrier

.LBB0_194:
	s_and_b64 vcc, exec, s[8:9]
	s_cbranch_vccz .LBB0_250
	s_cmp_gt_i32 s34, 4
	s_mov_b64 s[8:9], -1
	s_cbranch_scc0 .LBB0_235
	v_mov_b32_e32 v140, v201
	s_lshl_b32 s39, s50, 8
	v_ashrrev_i32_e32 v0, 31, v140
	v_lshrrev_b32_e32 v0, 26, v0
	v_add_u32_e32 v0, v140, v0
	v_ashrrev_i32_e32 v14, 6, v0
	v_bfe_i32 v0, v140, 27, 1
	v_lshlrev_b32_e32 v2, 4, v140
	v_lshrrev_b32_e32 v0, 22, v0
	v_add_u32_e32 v0, v2, v0
	v_and_b32_e32 v0, 0xfffffc00, v0
	v_sub_u32_e32 v0, v2, v0
	v_lshrrev_b32_e32 v3, 4, v0
	v_bitop3_b32 v3, v3, v0, 32 bitop3:0x6c
	v_ashrrev_i32_e32 v0, 31, v0
	v_lshrrev_b32_e32 v0, 26, v0
	v_lshlrev_b32_e32 v4, 3, v14
	v_add_u32_e32 v0, v3, v0
	v_and_b32_e32 v4, 0xfffff0, v4
	v_ashrrev_i32_e32 v17, 6, v0
	v_add_u32_e32 v0, v17, v4
	v_lshlrev_b32_e32 v4, 5, v14
	v_and_b32_e32 v16, 32, v4
	v_mul_i32_i24_e32 v4, 64, v17
	v_sub_u32_e32 v3, v3, v4
	v_ashrrev_i16_sdwa v3, v217, sext(v3) dst_sel:DWORD dst_unused:UNUSED_PAD src0_sel:DWORD src1_sel:BYTE_0
	v_add_u32_e32 v2, 0x2000, v2
	v_bfe_i32 v18, v3, 0, 16
	v_ashrrev_i32_e32 v3, 31, v2
	v_lshrrev_b32_e32 v3, 22, v3
	v_add_u32_e32 v3, v2, v3
	v_ashrrev_i32_e32 v20, 10, v3
	v_mul_i32_i24_e32 v3, 0x400, v20
	v_sub_u32_e32 v2, v2, v3
	v_lshrrev_b32_e32 v3, 4, v2
	v_bitop3_b32 v2, v3, v2, 32 bitop3:0x6c
	v_ashrrev_i32_e32 v4, 31, v2
	v_lshrrev_b32_e32 v4, 26, v4
	v_add_u32_e32 v4, v2, v4
	v_ashrrev_i32_e32 v19, 6, v140
	v_lshlrev_b32_e32 v3, 3, v20
	v_ashrrev_i32_e32 v22, 6, v4
	v_and_b32_e32 v4, 0xc0, v4
	v_readfirstlane_b32 s8, v19
	v_and_b32_e32 v3, 0xfffff0, v3
	v_sub_u32_e32 v2, v2, v4
	s_lshl_b32 s33, s8, 10
	s_movk_i32 s8, 0xb00
	v_add_u32_e32 v3, v22, v3
	v_ashrrev_i16_sdwa v2, v217, sext(v2) dst_sel:DWORD dst_unused:UNUSED_PAD src0_sel:DWORD src1_sel:BYTE_0
	s_lshl_b32 s36, s56, 8
	s_mul_i32 s10, s56, 0x160000
	v_readlane_b32 s16, v255, 7
	v_mul_lo_u32 v0, v0, s8
	v_bfe_i32 v23, v2, 0, 16
	v_mul_lo_u32 v2, v3, s8
	s_mul_hi_i32 s11, s36, 0x1600
	s_add_u32 s8, s16, s10
	v_readlane_b32 s17, v255, 9
	v_lshlrev_b32_e32 v5, 5, v20
	s_addc_u32 s9, s17, s11
	s_add_i32 s37, s33, 0
	v_or_b32_e32 v0, v0, v16
	v_and_b32_e32 v21, 32, v5
	s_add_i32 s42, s37, 0x10000
	v_add_lshl_u32 v0, v0, v18, 1
	v_or_b32_e32 v2, v2, v21
	s_mov_b32 m0, s42
	s_add_i32 s43, s37, 0x12000
	v_add_lshl_u32 v130, v2, v23, 1
	global_load_lds_dwordx4 v0, s[8:9]
	v_mov_b32_e32 v131, v1
	s_mov_b32 m0, s43
	s_mul_i32 s12, s50, 0x160000
	v_readlane_b32 s14, v253, 58
	v_lshl_add_u64 v[2:3], s[8:9], 0, v[0:1]
	v_lshl_add_u64 v[4:5], s[8:9], 0, v[130:131]
	global_load_lds_dwordx4 v130, s[8:9]
	s_mul_hi_i32 s13, s39, 0x1600
	v_readlane_b32 s15, v253, 59
	s_add_u32 s8, s14, s12
	s_addc_u32 s9, s15, s13
	s_mov_b32 m0, s37
	s_add_i32 s54, s37, 0x2000
	global_load_lds_dwordx4 v0, s[8:9]
	s_mov_b32 m0, s54
	s_waitcnt vmcnt(3)
	v_lshl_add_u64 v[6:7], s[8:9], 0, v[0:1]
	v_lshl_add_u64 v[8:9], s[8:9], 0, v[130:131]
	global_load_lds_dwordx4 v130, s[8:9]
	s_or_b32 s8, s36, 0x80
	s_mul_hi_i32 s9, s8, 0x1600
	s_mulk_i32 s8, 0x1600
	s_add_u32 s8, s16, s8
	s_addc_u32 s9, s17, s9
	s_add_i32 s55, s37, 0x14000
	s_mov_b32 m0, s55
	s_add_i32 s57, s37, 0x16000
	global_load_lds_dwordx4 v0, s[8:9]
	s_mov_b32 m0, s57
	s_or_b32 s38, s39, 0x80
	v_lshl_add_u64 v[10:11], s[8:9], 0, v[0:1]
	v_lshl_add_u64 v[12:13], s[8:9], 0, v[130:131]
	global_load_lds_dwordx4 v130, s[8:9]
	s_mul_i32 s8, s38, 0x1600
	s_mul_hi_i32 s9, s38, 0x1600
	s_add_u32 s8, s14, s8
	s_addc_u32 s9, s15, s9
	s_add_i32 s60, s37, 0x4000
	s_mov_b32 m0, s60
	s_add_i32 s61, s37, 0x6000
	global_load_lds_dwordx4 v0, s[8:9]
	s_mov_b32 m0, s61
	v_ashrrev_i32_e32 v15, 8, v140
	global_load_lds_dwordx4 v130, s[8:9]
	v_cmp_eq_u32_e32 vcc, 1, v15
	s_and_saveexec_b64 s[14:15], vcc
	s_cbranch_execz .LBB0_198
	s_barrier

.LBB0_235:
	s_and_b64 vcc, exec, s[8:9]
	s_cbranch_vccz .LBB0_249
	v_mov_b32_e32 v142, v201
	s_lshl_b32 s38, s56, 9
	v_ashrrev_i32_e32 v0, 31, v142
	v_lshrrev_b32_e32 v0, 26, v0
	v_add_u32_e32 v0, v142, v0
	v_ashrrev_i32_e32 v16, 6, v0
	v_bfe_i32 v0, v142, 27, 1
	v_lshlrev_b32_e32 v2, 4, v142
	v_lshrrev_b32_e32 v0, 22, v0
	v_add_u32_e32 v0, v2, v0
	v_and_b32_e32 v0, 0xfffffc00, v0
	v_sub_u32_e32 v0, v2, v0
	v_lshrrev_b32_e32 v3, 4, v0
	v_bitop3_b32 v3, v3, v0, 32 bitop3:0x6c
	v_ashrrev_i32_e32 v0, 31, v0
	v_lshrrev_b32_e32 v0, 26, v0
	v_add_u32_e32 v0, v3, v0
	v_ashrrev_i32_e32 v18, 6, v0
	v_mul_i32_i24_e32 v5, 64, v18
	v_sub_u32_e32 v3, v3, v5
	v_lshlrev_b32_e32 v4, 3, v16
	v_lshlrev_b32_e32 v0, 5, v16
	v_ashrrev_i16_sdwa v3, v217, sext(v3) dst_sel:DWORD dst_unused:UNUSED_PAD src0_sel:DWORD src1_sel:BYTE_0
	v_and_b32_e32 v4, 0x1ffff0, v4
	v_and_b32_e32 v0, 32, v0
	v_bfe_i32 v19, v3, 0, 16
	v_add_u32_e32 v0, v0, v19
	v_add_lshl_u32 v3, v18, v4, 11
	v_add_u32_e32 v2, 0x2000, v2
	v_lshl_add_u32 v0, v0, 1, v3
	v_ashrrev_i32_e32 v3, 31, v2
	v_lshrrev_b32_e32 v3, 22, v3
	v_add_u32_e32 v3, v2, v3
	v_ashrrev_i32_e32 v21, 10, v3
	v_mul_i32_i24_e32 v3, 0x400, v21
	v_sub_u32_e32 v2, v2, v3
	v_lshrrev_b32_e32 v3, 4, v2
	v_bitop3_b32 v2, v3, v2, 32 bitop3:0x6c
	v_ashrrev_i32_e32 v4, 31, v2
	v_ashrrev_i32_e32 v20, 6, v142
	v_lshrrev_b32_e32 v4, 26, v4
	v_readfirstlane_b32 s8, v20
	v_add_u32_e32 v4, v2, v4
	s_ashr_i32 s39, s38, 31
	s_lshl_b32 s33, s8, 10
	v_ashrrev_i32_e32 v22, 6, v4
	v_and_b32_e32 v4, 0xc0, v4
	s_lshl_b32 s10, s50, 8
	s_lshl_b64 s[12:13], s[38:39], 11
	v_readlane_b32 s16, v255, 10
	v_sub_u32_e32 v2, v2, v4
	s_add_u32 s8, s16, s12
	v_readlane_b32 s17, v255, 11
	v_lshlrev_b32_e32 v3, 3, v21
	v_lshlrev_b32_e32 v5, 5, v21
	v_ashrrev_i16_sdwa v2, v217, sext(v2) dst_sel:DWORD dst_unused:UNUSED_PAD src0_sel:DWORD src1_sel:BYTE_0
	s_addc_u32 s9, s17, s13
	s_add_i32 s36, s33, 0
	v_and_b32_e32 v3, 0x1ffff0, v3
	v_and_b32_e32 v5, 32, v5
	v_bfe_i32 v23, v2, 0, 16
	s_add_i32 s37, s36, 0x10000
	s_ashr_i32 s11, s10, 31
	v_add_u32_e32 v2, v5, v23
	v_add_lshl_u32 v3, v22, v3, 11
	s_mov_b32 m0, s37
	s_add_i32 s39, s36, 0x12000
	s_lshl_b64 s[14:15], s[10:11], 11
	v_lshl_add_u32 v2, v2, 1, v3
	global_load_lds_dwordx4 v0, s[8:9]
	v_mov_b32_e32 v3, v1
	s_mov_b32 m0, s39
	s_add_u32 s54, s44, s14
	v_lshl_add_u64 v[4:5], s[8:9], 0, v[0:1]
	s_waitcnt vmcnt(1)
	v_lshl_add_u64 v[6:7], s[8:9], 0, v[2:3]
	global_load_lds_dwordx4 v2, s[8:9]
	s_addc_u32 s55, s45, s15
	s_or_b32 s8, s38, 0x80
	s_ashr_i32 s9, s8, 31
	s_add_i32 s70, s36, 0x2000
	s_lshl_b64 s[8:9], s[8:9], 11
	s_mov_b32 m0, s36
	s_add_u32 s8, s16, s8
	global_load_lds_dwordx4 v0, s[54:55]
	s_mov_b32 m0, s70
	s_addc_u32 s9, s17, s9
	s_add_i32 s71, s36, 0x14000
	global_load_lds_dwordx4 v2, s[54:55]
	s_mov_b32 m0, s71
	s_add_i32 s72, s36, 0x16000
	global_load_lds_dwordx4 v0, s[8:9]
	s_mov_b32 m0, s72
	v_lshl_add_u64 v[12:13], s[8:9], 0, v[0:1]
	v_lshl_add_u64 v[14:15], s[8:9], 0, v[2:3]
	global_load_lds_dwordx4 v2, s[8:9]
	s_or_b32 s8, s10, 0x80
	s_ashr_i32 s9, s8, 31
	s_lshl_b64 s[42:43], s[8:9], 11
	s_add_u32 s60, s44, s42
	s_addc_u32 s61, s45, s43
	s_add_i32 s73, s36, 0x4000
	s_mov_b32 m0, s73
	s_add_i32 s88, s36, 0x6000
	global_load_lds_dwordx4 v0, s[60:61]
	s_mov_b32 m0, s88
	v_ashrrev_i32_e32 v17, 8, v142
	global_load_lds_dwordx4 v2, s[60:61]
	v_lshl_add_u64 v[8:9], s[54:55], 0, v[0:1]
	v_lshl_add_u64 v[10:11], s[54:55], 0, v[2:3]
	v_cmp_eq_u32_e32 vcc, 1, v17
	s_and_saveexec_b64 s[42:43], vcc
	s_cbranch_execz .LBB0_238
	s_barrier

.LBB0_251:
	s_and_b64 vcc, exec, s[8:9]
	s_cbranch_vccz .LBB0_385
	s_cmp_gt_i32 s34, 1
	s_mov_b64 s[8:9], -1
	s_cbranch_scc0 .LBB0_374
	s_cmp_gt_i32 s34, 2
	s_mov_b64 s[6:7], -1
	s_cbranch_scc0 .LBB0_293
	v_mov_b32_e32 v142, v201
	s_lshl_b32 s10, s56, 8
	v_ashrrev_i32_e32 v0, 31, v142
	v_lshrrev_b32_e32 v0, 26, v0
	v_add_u32_e32 v0, v142, v0
	v_ashrrev_i32_e32 v16, 6, v0
	v_bfe_i32 v0, v142, 27, 1
	v_lshlrev_b32_e32 v2, 4, v142
	v_lshrrev_b32_e32 v0, 22, v0
	v_add_u32_e32 v0, v2, v0
	v_and_b32_e32 v0, 0xfffffc00, v0
	v_sub_u32_e32 v0, v2, v0
	v_lshrrev_b32_e32 v3, 4, v0
	v_bitop3_b32 v3, v3, v0, 32 bitop3:0x6c
	v_ashrrev_i32_e32 v0, 31, v0
	v_lshrrev_b32_e32 v0, 26, v0
	v_lshlrev_b32_e32 v4, 3, v16
	v_add_u32_e32 v0, v3, v0
	v_and_b32_e32 v4, 0x1ffff0, v4
	v_ashrrev_i32_e32 v18, 6, v0
	v_add_u32_e32 v0, v18, v4
	v_lshlrev_b32_e32 v4, 5, v16
	v_and_b32_e32 v19, 32, v4
	v_mul_i32_i24_e32 v4, 64, v18
	v_sub_u32_e32 v3, v3, v4
	v_ashrrev_i16_sdwa v3, v217, sext(v3) dst_sel:DWORD dst_unused:UNUSED_PAD src0_sel:DWORD src1_sel:BYTE_0
	v_add_u32_e32 v2, 0x2000, v2
	v_bfe_i32 v20, v3, 0, 16
	v_ashrrev_i32_e32 v3, 31, v2
	v_lshrrev_b32_e32 v3, 22, v3
	v_add_u32_e32 v3, v2, v3
	v_ashrrev_i32_e32 v22, 10, v3
	v_mul_i32_i24_e32 v3, 0x400, v22
	v_sub_u32_e32 v2, v2, v3
	v_lshrrev_b32_e32 v3, 4, v2
	v_bitop3_b32 v2, v3, v2, 32 bitop3:0x6c
	v_ashrrev_i32_e32 v21, 6, v142
	v_ashrrev_i32_e32 v4, 31, v2
	v_readfirstlane_b32 s6, v21
	v_lshrrev_b32_e32 v4, 26, v4
	s_ashr_i32 s11, s10, 31
	s_lshl_b32 s33, s6, 10
	v_add_u32_e32 v4, v2, v4
	s_lshl_b32 s8, s50, 8
	s_lshl_b64 s[12:13], s[10:11], 11
	v_readlane_b32 s18, v255, 15
	v_lshlrev_b32_e32 v3, 3, v22
	v_ashrrev_i32_e32 v23, 6, v4
	v_and_b32_e32 v4, 0xc0, v4
	s_add_u32 s6, s18, s12
	v_readlane_b32 s19, v255, 16
	v_and_b32_e32 v3, 0x1ffff0, v3
	v_lshlrev_b32_e32 v5, 5, v22
	v_sub_u32_e32 v2, v2, v4
	s_addc_u32 s7, s19, s13
	s_add_i32 s11, s33, 0
	v_lshl_or_b32 v0, v0, 10, v19
	v_add_u32_e32 v3, v23, v3
	v_and_b32_e32 v24, 32, v5
	v_ashrrev_i16_sdwa v2, v217, sext(v2) dst_sel:DWORD dst_unused:UNUSED_PAD src0_sel:DWORD src1_sel:BYTE_0
	s_add_i32 s36, s11, 0x10000
	v_add_lshl_u32 v0, v0, v20, 1
	v_bfe_i32 v25, v2, 0, 16
	v_lshl_or_b32 v2, v3, 10, v24
	s_mov_b32 m0, s36
	s_add_i32 s37, s11, 0x12000
	s_ashr_i32 s9, s8, 31
	v_add_lshl_u32 v2, v2, v25, 1
	global_load_lds_dwordx4 v0, s[6:7]
	v_mov_b32_e32 v3, v1
	s_mov_b32 m0, s37
	s_lshl_b64 s[14:15], s[8:9], 11
	v_readlane_b32 s16, v255, 12
	v_lshl_add_u64 v[4:5], s[6:7], 0, v[0:1]
	s_waitcnt vmcnt(1)
	v_lshl_add_u64 v[6:7], s[6:7], 0, v[2:3]
	global_load_lds_dwordx4 v2, s[6:7]
	s_add_u32 s6, s16, s14
	v_readlane_b32 s17, v255, 14
	s_addc_u32 s7, s17, s15
	s_mov_b32 m0, s11
	s_add_i32 s9, s11, 0x2000
	global_load_lds_dwordx4 v0, s[6:7]
	s_mov_b32 m0, s9
	v_lshl_add_u64 v[8:9], s[6:7], 0, v[0:1]
	v_lshl_add_u64 v[10:11], s[6:7], 0, v[2:3]
	global_load_lds_dwordx4 v2, s[6:7]
	s_or_b32 s6, s10, 0x80
	s_ashr_i32 s7, s6, 31
	s_lshl_b64 s[6:7], s[6:7], 11
	s_add_u32 s6, s18, s6
	s_addc_u32 s7, s19, s7
	s_add_i32 s54, s11, 0x14000
	s_mov_b32 m0, s54
	s_add_i32 s55, s11, 0x16000
	global_load_lds_dwordx4 v0, s[6:7]
	s_mov_b32 m0, s55
	v_lshl_add_u64 v[12:13], s[6:7], 0, v[0:1]
	v_lshl_add_u64 v[14:15], s[6:7], 0, v[2:3]
	global_load_lds_dwordx4 v2, s[6:7]
	s_or_b32 s6, s8, 0x80
	s_ashr_i32 s7, s6, 31
	s_lshl_b64 s[38:39], s[6:7], 11
	s_add_u32 s38, s16, s38
	s_addc_u32 s39, s17, s39
	s_add_i32 s7, s11, 0x4000
	s_mov_b32 m0, s7
	s_add_i32 s57, s11, 0x6000
	global_load_lds_dwordx4 v0, s[38:39]
	s_mov_b32 m0, s57
	v_ashrrev_i32_e32 v17, 8, v142
	global_load_lds_dwordx4 v2, s[38:39]
	v_cmp_eq_u32_e32 vcc, 1, v17
	s_and_saveexec_b64 s[42:43], vcc
	s_cbranch_execz .LBB0_256
	s_barrier

.LBB0_374:
	s_mov_b64 s[6:7], 0
	s_and_b64 vcc, exec, s[8:9]
	s_cbranch_vccz .LBB0_385
	s_cmp_gt_i32 s34, 0
	s_mov_b64 s[8:9], -1
	s_cbranch_scc0 .LBB0_383
	v_mov_b32_e32 v142, v201
	s_lshl_b32 s10, s56, 8
	v_ashrrev_i32_e32 v0, 31, v142
	v_lshrrev_b32_e32 v0, 26, v0
	v_add_u32_e32 v0, v142, v0
	v_ashrrev_i32_e32 v16, 6, v0
	v_bfe_i32 v0, v142, 27, 1
	v_lshlrev_b32_e32 v2, 4, v142
	v_lshrrev_b32_e32 v0, 22, v0
	v_add_u32_e32 v0, v2, v0
	v_and_b32_e32 v0, 0xfffffc00, v0
	v_sub_u32_e32 v0, v2, v0
	v_lshrrev_b32_e32 v3, 4, v0
	v_bitop3_b32 v3, v3, v0, 32 bitop3:0x6c
	v_ashrrev_i32_e32 v0, 31, v0
	v_lshrrev_b32_e32 v0, 26, v0
	v_add_u32_e32 v0, v3, v0
	v_ashrrev_i32_e32 v18, 6, v0
	v_mul_i32_i24_e32 v5, 64, v18
	v_sub_u32_e32 v3, v3, v5
	v_lshlrev_b32_e32 v4, 3, v16
	v_lshlrev_b32_e32 v0, 5, v16
	v_ashrrev_i16_sdwa v3, v217, sext(v3) dst_sel:DWORD dst_unused:UNUSED_PAD src0_sel:DWORD src1_sel:BYTE_0
	v_and_b32_e32 v4, 0x1ffff0, v4
	v_and_b32_e32 v0, 32, v0
	v_bfe_i32 v19, v3, 0, 16
	v_add_u32_e32 v0, v0, v19
	v_add_lshl_u32 v3, v18, v4, 11
	v_add_u32_e32 v2, 0x2000, v2
	v_lshl_add_u32 v0, v0, 1, v3
	v_ashrrev_i32_e32 v3, 31, v2
	v_lshrrev_b32_e32 v3, 22, v3
	v_add_u32_e32 v3, v2, v3
	v_ashrrev_i32_e32 v21, 10, v3
	v_mul_i32_i24_e32 v3, 0x400, v21
	v_sub_u32_e32 v2, v2, v3
	v_lshrrev_b32_e32 v3, 4, v2
	v_bitop3_b32 v2, v3, v2, 32 bitop3:0x6c
	v_ashrrev_i32_e32 v4, 31, v2
	v_ashrrev_i32_e32 v20, 6, v142
	v_lshrrev_b32_e32 v4, 26, v4
	v_readfirstlane_b32 s6, v20
	v_add_u32_e32 v4, v2, v4
	s_ashr_i32 s11, s10, 31
	s_lshl_b32 s33, s6, 10
	v_ashrrev_i32_e32 v22, 6, v4
	v_and_b32_e32 v4, 0xc0, v4
	s_lshl_b32 s8, s50, 8
	s_lshl_b64 s[12:13], s[10:11], 11
	v_readlane_b32 s16, v255, 25
	v_sub_u32_e32 v2, v2, v4
	s_add_u32 s6, s16, s12
	v_readlane_b32 s17, v255, 26
	v_lshlrev_b32_e32 v3, 3, v21
	v_lshlrev_b32_e32 v5, 5, v21
	v_ashrrev_i16_sdwa v2, v217, sext(v2) dst_sel:DWORD dst_unused:UNUSED_PAD src0_sel:DWORD src1_sel:BYTE_0
	s_addc_u32 s7, s17, s13
	s_add_i32 s11, s33, 0
	v_and_b32_e32 v3, 0x1ffff0, v3
	v_and_b32_e32 v5, 32, v5
	v_bfe_i32 v23, v2, 0, 16
	s_add_i32 s36, s11, 0x10000
	v_add_u32_e32 v2, v5, v23
	v_add_lshl_u32 v3, v22, v3, 11
	s_mov_b32 m0, s36
	s_add_i32 s37, s11, 0x12000
	s_ashr_i32 s9, s8, 31
	v_lshl_add_u32 v2, v2, 1, v3
	global_load_lds_dwordx4 v0, s[6:7]
	v_mov_b32_e32 v3, v1
	s_mov_b32 m0, s37
	s_lshl_b64 s[14:15], s[8:9], 11
	v_lshl_add_u64 v[4:5], s[6:7], 0, v[0:1]
	s_waitcnt vmcnt(1)
	v_lshl_add_u64 v[6:7], s[6:7], 0, v[2:3]
	global_load_lds_dwordx4 v2, s[6:7]
	s_add_u32 s6, s44, s14
	s_addc_u32 s7, s45, s15
	s_mov_b32 m0, s11
	s_add_i32 s9, s11, 0x2000
	global_load_lds_dwordx4 v0, s[6:7]
	s_mov_b32 m0, s9
	v_lshl_add_u64 v[8:9], s[6:7], 0, v[0:1]
	v_lshl_add_u64 v[10:11], s[6:7], 0, v[2:3]
	global_load_lds_dwordx4 v2, s[6:7]
	s_or_b32 s6, s10, 0x80
	s_ashr_i32 s7, s6, 31
	s_lshl_b64 s[6:7], s[6:7], 11
	s_add_u32 s6, s16, s6
	s_addc_u32 s7, s17, s7
	s_add_i32 s51, s11, 0x14000
	s_mov_b32 m0, s51
	s_add_i32 s54, s11, 0x16000
	global_load_lds_dwordx4 v0, s[6:7]
	s_mov_b32 m0, s54
	v_lshl_add_u64 v[12:13], s[6:7], 0, v[0:1]
	v_lshl_add_u64 v[14:15], s[6:7], 0, v[2:3]
	global_load_lds_dwordx4 v2, s[6:7]
	s_or_b32 s6, s8, 0x80
	s_ashr_i32 s7, s6, 31
	s_lshl_b64 s[38:39], s[6:7], 11
	s_add_u32 s38, s44, s38
	s_addc_u32 s39, s45, s39
	s_add_i32 s7, s11, 0x4000
	s_mov_b32 m0, s7
	s_add_i32 s55, s11, 0x6000
	global_load_lds_dwordx4 v0, s[38:39]
	s_mov_b32 m0, s55
	v_ashrrev_i32_e32 v17, 8, v142
	global_load_lds_dwordx4 v2, s[38:39]
	v_cmp_eq_u32_e32 vcc, 1, v17
	s_and_saveexec_b64 s[42:43], vcc
	s_cbranch_execz .LBB0_378
	s_barrier

.LBB0_404:
	v_mov_b32_e32 v142, v201
	s_lshl_b32 s10, s56, 8
	v_ashrrev_i32_e32 v0, 31, v142
	v_lshrrev_b32_e32 v0, 26, v0
	v_add_u32_e32 v0, v142, v0
	v_ashrrev_i32_e32 v16, 6, v0
	v_bfe_i32 v0, v142, 27, 1
	v_lshlrev_b32_e32 v2, 4, v142
	v_lshrrev_b32_e32 v0, 22, v0
	v_add_u32_e32 v0, v2, v0
	v_and_b32_e32 v0, 0xfffffc00, v0
	v_sub_u32_e32 v0, v2, v0
	v_lshrrev_b32_e32 v3, 4, v0
	v_bitop3_b32 v3, v3, v0, 32 bitop3:0x6c
	v_ashrrev_i32_e32 v0, 31, v0
	v_lshrrev_b32_e32 v0, 26, v0
	v_add_u32_e32 v0, v3, v0
	v_ashrrev_i32_e32 v18, 6, v0
	v_mul_i32_i24_e32 v5, 64, v18
	v_sub_u32_e32 v3, v3, v5
	v_lshlrev_b32_e32 v4, 3, v16
	v_lshlrev_b32_e32 v0, 5, v16
	v_ashrrev_i16_sdwa v3, v217, sext(v3) dst_sel:DWORD dst_unused:UNUSED_PAD src0_sel:DWORD src1_sel:BYTE_0
	v_and_b32_e32 v4, 0x1ffff0, v4
	v_and_b32_e32 v0, 32, v0
	v_bfe_i32 v19, v3, 0, 16
	v_add_u32_e32 v0, v0, v19
	v_add_lshl_u32 v3, v18, v4, 11
	v_add_u32_e32 v2, 0x2000, v2
	v_lshl_add_u32 v0, v0, 1, v3
	v_ashrrev_i32_e32 v3, 31, v2
	v_lshrrev_b32_e32 v3, 22, v3
	v_add_u32_e32 v3, v2, v3
	v_ashrrev_i32_e32 v21, 10, v3
	v_mul_i32_i24_e32 v3, 0x400, v21
	v_sub_u32_e32 v2, v2, v3
	v_lshrrev_b32_e32 v3, 4, v2
	v_bitop3_b32 v2, v3, v2, 32 bitop3:0x6c
	v_ashrrev_i32_e32 v4, 31, v2
	v_ashrrev_i32_e32 v20, 6, v142
	v_lshrrev_b32_e32 v4, 26, v4
	v_readfirstlane_b32 s6, v20
	v_add_u32_e32 v4, v2, v4
	s_ashr_i32 s11, s10, 31
	s_lshl_b32 s33, s6, 10
	v_ashrrev_i32_e32 v22, 6, v4
	v_and_b32_e32 v4, 0xc0, v4
	s_lshl_b32 s8, s50, 8
	s_lshl_b64 s[12:13], s[10:11], 11
	v_readlane_b32 s16, v255, 31
	v_sub_u32_e32 v2, v2, v4
	s_add_u32 s6, s16, s12
	v_readlane_b32 s17, v255, 33
	v_lshlrev_b32_e32 v3, 3, v21
	v_lshlrev_b32_e32 v5, 5, v21
	v_ashrrev_i16_sdwa v2, v217, sext(v2) dst_sel:DWORD dst_unused:UNUSED_PAD src0_sel:DWORD src1_sel:BYTE_0
	s_addc_u32 s7, s17, s13
	s_add_i32 s11, s33, 0
	v_and_b32_e32 v3, 0x1ffff0, v3
	v_and_b32_e32 v5, 32, v5
	v_bfe_i32 v23, v2, 0, 16
	s_add_i32 s36, s11, 0x10000
	v_add_u32_e32 v2, v5, v23
	v_add_lshl_u32 v3, v22, v3, 11
	s_mov_b32 m0, s36
	s_add_i32 s37, s11, 0x12000
	s_ashr_i32 s9, s8, 31
	v_lshl_add_u32 v2, v2, 1, v3
	global_load_lds_dwordx4 v0, s[6:7]
	v_mov_b32_e32 v3, v1
	s_mov_b32 m0, s37
	s_lshl_b64 s[14:15], s[8:9], 11
	v_lshl_add_u64 v[4:5], s[6:7], 0, v[0:1]
	s_waitcnt vmcnt(1)
	v_lshl_add_u64 v[6:7], s[6:7], 0, v[2:3]
	global_load_lds_dwordx4 v2, s[6:7]
	s_add_u32 s6, s44, s14
	s_addc_u32 s7, s45, s15
	s_mov_b32 m0, s11
	s_add_i32 s9, s11, 0x2000
	global_load_lds_dwordx4 v0, s[6:7]
	s_mov_b32 m0, s9
	v_lshl_add_u64 v[8:9], s[6:7], 0, v[0:1]
	v_lshl_add_u64 v[10:11], s[6:7], 0, v[2:3]
	global_load_lds_dwordx4 v2, s[6:7]
	s_or_b32 s6, s10, 0x80
	s_ashr_i32 s7, s6, 31
	s_lshl_b64 s[6:7], s[6:7], 11
	s_add_u32 s6, s16, s6
	s_addc_u32 s7, s17, s7
	s_add_i32 s51, s11, 0x14000
	s_mov_b32 m0, s51
	s_add_i32 s54, s11, 0x16000
	global_load_lds_dwordx4 v0, s[6:7]
	s_mov_b32 m0, s54
	v_lshl_add_u64 v[12:13], s[6:7], 0, v[0:1]
	v_lshl_add_u64 v[14:15], s[6:7], 0, v[2:3]
	global_load_lds_dwordx4 v2, s[6:7]
	s_or_b32 s6, s8, 0x80
	s_ashr_i32 s7, s6, 31
	s_lshl_b64 s[38:39], s[6:7], 11
	s_add_u32 s38, s44, s38
	s_addc_u32 s39, s45, s39
	s_add_i32 s7, s11, 0x4000
	s_mov_b32 m0, s7
	s_add_i32 s55, s11, 0x6000
	global_load_lds_dwordx4 v0, s[38:39]
	s_mov_b32 m0, s55
	v_ashrrev_i32_e32 v17, 8, v142
	global_load_lds_dwordx4 v2, s[38:39]
	v_cmp_eq_u32_e32 vcc, 1, v17
	s_and_saveexec_b64 s[42:43], vcc
	s_cbranch_execz .LBB0_406
	s_barrier

.LBB0_411:
	v_mov_b32_e32 v142, v201
	s_lshl_b32 s15, s50, 8
	v_ashrrev_i32_e32 v0, 31, v142
	v_lshrrev_b32_e32 v0, 26, v0
	v_add_u32_e32 v0, v142, v0
	v_ashrrev_i32_e32 v16, 6, v0
	v_bfe_i32 v0, v142, 27, 1
	v_lshlrev_b32_e32 v2, 4, v142
	v_lshrrev_b32_e32 v0, 22, v0
	v_add_u32_e32 v0, v2, v0
	v_and_b32_e32 v0, 0xfffffc00, v0
	v_sub_u32_e32 v0, v2, v0
	v_lshrrev_b32_e32 v3, 4, v0
	v_bitop3_b32 v3, v3, v0, 32 bitop3:0x6c
	v_ashrrev_i32_e32 v0, 31, v0
	v_lshrrev_b32_e32 v0, 26, v0
	v_lshlrev_b32_e32 v4, 3, v16
	v_add_u32_e32 v0, v3, v0
	v_and_b32_e32 v4, 0x7ffff0, v4
	v_ashrrev_i32_e32 v18, 6, v0
	v_add_u32_e32 v0, v18, v4
	v_lshlrev_b32_e32 v4, 5, v16
	v_and_b32_e32 v19, 32, v4
	v_mul_i32_i24_e32 v4, 64, v18
	v_sub_u32_e32 v3, v3, v4
	v_ashrrev_i16_sdwa v3, v217, sext(v3) dst_sel:DWORD dst_unused:UNUSED_PAD src0_sel:DWORD src1_sel:BYTE_0
	v_add_u32_e32 v2, 0x2000, v2
	v_bfe_i32 v20, v3, 0, 16
	v_ashrrev_i32_e32 v3, 31, v2
	v_lshrrev_b32_e32 v3, 22, v3
	v_add_u32_e32 v3, v2, v3
	v_ashrrev_i32_e32 v22, 10, v3
	v_mul_i32_i24_e32 v3, 0x400, v22
	v_sub_u32_e32 v2, v2, v3
	v_lshrrev_b32_e32 v3, 4, v2
	v_bitop3_b32 v2, v3, v2, 32 bitop3:0x6c
	v_ashrrev_i32_e32 v4, 31, v2
	v_lshrrev_b32_e32 v4, 26, v4
	v_add_u32_e32 v4, v2, v4
	v_ashrrev_i32_e32 v21, 6, v142
	v_lshlrev_b32_e32 v3, 3, v22
	v_ashrrev_i32_e32 v23, 6, v4
	v_and_b32_e32 v4, 0xc0, v4
	v_readfirstlane_b32 s6, v21
	v_and_b32_e32 v3, 0x7ffff0, v3
	v_sub_u32_e32 v2, v2, v4
	s_lshl_b32 s33, s6, 10
	s_movk_i32 s6, 0x600
	v_add_u32_e32 v3, v23, v3
	v_ashrrev_i16_sdwa v2, v217, sext(v2) dst_sel:DWORD dst_unused:UNUSED_PAD src0_sel:DWORD src1_sel:BYTE_0
	v_mul_lo_u32 v0, v0, s6
	v_bfe_i32 v25, v2, 0, 16
	v_mul_lo_u32 v2, v3, s6
	s_lshl_b32 s36, s56, 8
	s_mul_i32 s6, s56, 0xc0000
	v_readlane_b32 s12, v255, 27
	s_mul_hi_i32 s7, s36, 0xc00
	s_add_u32 s8, s12, s6
	v_readlane_b32 s13, v255, 29
	v_lshlrev_b32_e32 v5, 5, v22
	s_addc_u32 s9, s13, s7
	s_add_i32 s37, s33, 0
	v_or_b32_e32 v0, v0, v19
	v_and_b32_e32 v24, 32, v5
	s_add_i32 s38, s37, 0x10000
	v_add_lshl_u32 v0, v0, v20, 1
	v_or_b32_e32 v2, v2, v24
	s_mov_b32 m0, s38
	s_add_i32 s39, s37, 0x12000
	v_add_lshl_u32 v2, v2, v25, 1
	global_load_lds_dwordx4 v0, s[8:9]
	v_mov_b32_e32 v3, v1
	s_mov_b32 m0, s39
	v_lshl_add_u64 v[4:5], s[8:9], 0, v[0:1]
	s_waitcnt vmcnt(1)
	v_lshl_add_u64 v[6:7], s[8:9], 0, v[2:3]
	global_load_lds_dwordx4 v2, s[8:9]
	s_mul_i32 s8, s50, 0xc0000
	s_mul_hi_i32 s9, s15, 0xc00
	s_add_u32 s10, s30, s8
	s_addc_u32 s11, s31, s9
	s_mov_b32 m0, s37
	s_add_i32 s42, s37, 0x2000
	global_load_lds_dwordx4 v0, s[10:11]
	s_mov_b32 m0, s42
	v_lshl_add_u64 v[8:9], s[10:11], 0, v[0:1]
	v_lshl_add_u64 v[10:11], s[10:11], 0, v[2:3]
	global_load_lds_dwordx4 v2, s[10:11]
	s_or_b32 s10, s36, 0x80
	s_mul_hi_i32 s11, s10, 0xc00
	s_mulk_i32 s10, 0xc00
	s_add_u32 s10, s12, s10
	s_addc_u32 s11, s13, s11
	s_add_i32 s43, s37, 0x14000
	s_mov_b32 m0, s43
	s_add_i32 s51, s37, 0x16000
	global_load_lds_dwordx4 v0, s[10:11]
	s_mov_b32 m0, s51
	s_or_b32 s14, s15, 0x80
	v_lshl_add_u64 v[12:13], s[10:11], 0, v[0:1]
	v_lshl_add_u64 v[14:15], s[10:11], 0, v[2:3]
	global_load_lds_dwordx4 v2, s[10:11]
	s_mul_i32 s10, s14, 0xc00
	s_mul_hi_i32 s11, s14, 0xc00
	s_add_u32 s10, s30, s10
	s_addc_u32 s11, s31, s11
	s_add_i32 s54, s37, 0x4000
	s_mov_b32 m0, s54
	s_add_i32 s55, s37, 0x6000
	global_load_lds_dwordx4 v0, s[10:11]
	s_mov_b32 m0, s55
	v_ashrrev_i32_e32 v17, 8, v142
	global_load_lds_dwordx4 v2, s[10:11]
	v_cmp_eq_u32_e32 vcc, 1, v17
	s_and_saveexec_b64 s[12:13], vcc
	s_cbranch_execz .LBB0_413
	s_barrier

.LBB0_1030:
	s_and_b64 vcc, exec, s[10:11]
	s_cbranch_vccz .LBB0_1070
	v_mov_b32_e32 v140, v201
	s_lshl_b32 s17, s30, 8
	v_ashrrev_i32_e32 v0, 31, v140
	v_lshrrev_b32_e32 v0, 26, v0
	v_add_u32_e32 v0, v140, v0
	v_ashrrev_i32_e32 v14, 6, v0
	v_bfe_i32 v0, v140, 27, 1
	v_lshlrev_b32_e32 v2, 4, v140
	v_lshrrev_b32_e32 v0, 22, v0
	v_add_u32_e32 v0, v2, v0
	v_and_b32_e32 v0, 0xfffffc00, v0
	v_sub_u32_e32 v0, v2, v0
	v_lshrrev_b32_e32 v3, 4, v0
	v_bitop3_b32 v3, v3, v0, 32 bitop3:0x6c
	v_ashrrev_i32_e32 v0, 31, v0
	v_lshrrev_b32_e32 v0, 26, v0
	v_lshlrev_b32_e32 v4, 3, v14
	v_add_u32_e32 v0, v3, v0
	v_and_b32_e32 v4, 0xfffff0, v4
	v_ashrrev_i32_e32 v16, 6, v0
	v_add_u32_e32 v0, v16, v4
	v_lshlrev_b32_e32 v4, 5, v14
	v_and_b32_e32 v15, 32, v4
	v_mul_i32_i24_e32 v4, 64, v16
	v_sub_u32_e32 v3, v3, v4
	v_ashrrev_i16_sdwa v3, v217, sext(v3) dst_sel:DWORD dst_unused:UNUSED_PAD src0_sel:DWORD src1_sel:BYTE_0
	v_add_u32_e32 v2, 0x2000, v2
	v_bfe_i32 v17, v3, 0, 16
	v_ashrrev_i32_e32 v3, 31, v2
	v_lshrrev_b32_e32 v3, 22, v3
	v_add_u32_e32 v3, v2, v3
	v_ashrrev_i32_e32 v20, 10, v3
	v_mul_i32_i24_e32 v3, 0x400, v20
	v_sub_u32_e32 v2, v2, v3
	v_lshrrev_b32_e32 v3, 4, v2
	v_bitop3_b32 v2, v3, v2, 32 bitop3:0x6c
	v_ashrrev_i32_e32 v4, 31, v2
	v_lshrrev_b32_e32 v4, 26, v4
	v_add_u32_e32 v4, v2, v4
	v_ashrrev_i32_e32 v19, 6, v140
	v_lshlrev_b32_e32 v3, 3, v20
	v_ashrrev_i32_e32 v22, 6, v4
	v_and_b32_e32 v4, 0xc0, v4
	v_readfirstlane_b32 s7, v19
	v_and_b32_e32 v3, 0xfffff0, v3
	v_sub_u32_e32 v2, v2, v4
	s_lshl_b32 s33, s7, 10
	s_movk_i32 s7, 0xb00
	v_add_u32_e32 v3, v22, v3
	v_ashrrev_i16_sdwa v2, v217, sext(v2) dst_sel:DWORD dst_unused:UNUSED_PAD src0_sel:DWORD src1_sel:BYTE_0
	v_mul_lo_u32 v0, v0, s7
	v_bfe_i32 v23, v2, 0, 16
	v_mul_lo_u32 v2, v3, s7
	s_lshl_b32 s7, s6, 8
	s_mul_i32 s44, s6, 0x160000
	v_readlane_b32 s16, v254, 49
	s_mul_hi_i32 s45, s7, 0x1600
	s_add_u32 s10, s16, s44
	v_readlane_b32 s20, v254, 51
	v_lshlrev_b32_e32 v5, 5, v20
	s_addc_u32 s11, s20, s45
	s_add_i32 s22, s33, 0
	v_or_b32_e32 v0, v0, v15
	v_and_b32_e32 v21, 32, v5
	s_add_i32 s23, s22, 0x10000
	v_add_lshl_u32 v0, v0, v17, 1
	v_or_b32_e32 v2, v2, v21
	s_mov_b32 m0, s23
	s_add_i32 s24, s22, 0x12000
	v_add_lshl_u32 v130, v2, v23, 1
	global_load_lds_dwordx4 v0, s[10:11]
	v_mov_b32_e32 v131, v1
	s_mov_b32 m0, s24
	s_mul_i32 s12, s30, 0x160000
	v_readlane_b32 s14, v255, 27
	v_lshl_add_u64 v[2:3], s[10:11], 0, v[0:1]
	v_lshl_add_u64 v[4:5], s[10:11], 0, v[130:131]
	global_load_lds_dwordx4 v130, s[10:11]
	s_mul_hi_i32 s13, s17, 0x1600
	v_readlane_b32 s15, v255, 28
	s_add_u32 s10, s14, s12
	s_addc_u32 s11, s15, s13
	s_mov_b32 m0, s22
	s_add_i32 s25, s22, 0x2000
	global_load_lds_dwordx4 v0, s[10:11]
	s_mov_b32 m0, s25
	s_waitcnt vmcnt(3)
	v_lshl_add_u64 v[6:7], s[10:11], 0, v[0:1]
	v_lshl_add_u64 v[8:9], s[10:11], 0, v[130:131]
	global_load_lds_dwordx4 v130, s[10:11]
	s_or_b32 s10, s7, 0x80
	s_mul_hi_i32 s11, s10, 0x1600
	s_mulk_i32 s10, 0x1600
	s_add_u32 s10, s16, s10
	s_addc_u32 s11, s20, s11
	s_add_i32 s36, s22, 0x14000
	s_mov_b32 m0, s36
	s_add_i32 s37, s22, 0x16000
	global_load_lds_dwordx4 v0, s[10:11]
	s_mov_b32 m0, s37
	s_or_b32 s16, s17, 0x80
	v_lshl_add_u64 v[10:11], s[10:11], 0, v[0:1]
	v_lshl_add_u64 v[12:13], s[10:11], 0, v[130:131]
	global_load_lds_dwordx4 v130, s[10:11]
	s_mul_i32 s10, s16, 0x1600
	s_mul_hi_i32 s11, s16, 0x1600
	s_add_u32 s10, s14, s10
	s_addc_u32 s11, s15, s11
	s_add_i32 s42, s22, 0x4000
	s_mov_b32 m0, s42
	s_add_i32 s43, s22, 0x6000
	global_load_lds_dwordx4 v0, s[10:11]
	s_mov_b32 m0, s43
	v_ashrrev_i32_e32 v18, 8, v140
	global_load_lds_dwordx4 v130, s[10:11]
	v_cmp_eq_u32_e32 vcc, 1, v18
	s_and_saveexec_b64 s[14:15], vcc
	s_cbranch_execz .LBB0_1033
	s_barrier

.LBB0_1071:
	s_and_b64 vcc, exec, s[10:11]
	s_cbranch_vccz .LBB0_1085
	v_mov_b32_e32 v142, v201
	s_lshl_b32 s60, s6, 9
	v_ashrrev_i32_e32 v0, 31, v142
	v_lshrrev_b32_e32 v0, 26, v0
	v_add_u32_e32 v0, v142, v0
	v_ashrrev_i32_e32 v16, 6, v0
	v_bfe_i32 v0, v142, 27, 1
	v_lshlrev_b32_e32 v2, 4, v142
	v_lshrrev_b32_e32 v0, 22, v0
	v_add_u32_e32 v0, v2, v0
	v_and_b32_e32 v0, 0xfffffc00, v0
	v_sub_u32_e32 v0, v2, v0
	v_lshrrev_b32_e32 v3, 4, v0
	v_bitop3_b32 v3, v3, v0, 32 bitop3:0x6c
	v_ashrrev_i32_e32 v0, 31, v0
	v_lshrrev_b32_e32 v0, 26, v0
	v_add_u32_e32 v0, v3, v0
	v_ashrrev_i32_e32 v18, 6, v0
	v_mul_i32_i24_e32 v5, 64, v18
	v_sub_u32_e32 v3, v3, v5
	v_lshlrev_b32_e32 v4, 3, v16
	v_lshlrev_b32_e32 v0, 5, v16
	v_ashrrev_i16_sdwa v3, v217, sext(v3) dst_sel:DWORD dst_unused:UNUSED_PAD src0_sel:DWORD src1_sel:BYTE_0
	v_and_b32_e32 v4, 0x1ffff0, v4
	v_and_b32_e32 v0, 32, v0
	v_bfe_i32 v19, v3, 0, 16
	v_add_u32_e32 v0, v0, v19
	v_add_lshl_u32 v3, v18, v4, 11
	v_add_u32_e32 v2, 0x2000, v2
	v_lshl_add_u32 v0, v0, 1, v3
	v_ashrrev_i32_e32 v3, 31, v2
	v_lshrrev_b32_e32 v3, 22, v3
	v_add_u32_e32 v3, v2, v3
	v_ashrrev_i32_e32 v21, 10, v3
	v_mul_i32_i24_e32 v3, 0x400, v21
	v_sub_u32_e32 v2, v2, v3
	v_lshrrev_b32_e32 v3, 4, v2
	v_bitop3_b32 v2, v3, v2, 32 bitop3:0x6c
	v_ashrrev_i32_e32 v4, 31, v2
	v_ashrrev_i32_e32 v20, 6, v142
	v_lshrrev_b32_e32 v4, 26, v4
	v_readfirstlane_b32 s7, v20
	v_add_u32_e32 v4, v2, v4
	s_ashr_i32 s61, s60, 31
	s_lshl_b32 s33, s7, 10
	v_ashrrev_i32_e32 v22, 6, v4
	v_and_b32_e32 v4, 0xc0, v4
	s_lshl_b32 s12, s30, 8
	s_lshl_b64 s[24:25], s[60:61], 11
	v_readlane_b32 s7, v255, 9
	v_sub_u32_e32 v2, v2, v4
	s_add_u32 s10, s7, s24
	v_readlane_b32 s16, v255, 15
	v_lshlrev_b32_e32 v3, 3, v21
	v_lshlrev_b32_e32 v5, 5, v21
	v_ashrrev_i16_sdwa v2, v217, sext(v2) dst_sel:DWORD dst_unused:UNUSED_PAD src0_sel:DWORD src1_sel:BYTE_0
	s_addc_u32 s11, s16, s25
	s_add_i32 s36, s33, 0
	v_and_b32_e32 v3, 0x1ffff0, v3
	v_and_b32_e32 v5, 32, v5
	v_bfe_i32 v23, v2, 0, 16
	s_add_i32 s37, s36, 0x10000
	s_ashr_i32 s13, s12, 31
	v_add_u32_e32 v2, v5, v23
	v_add_lshl_u32 v3, v22, v3, 11
	s_mov_b32 m0, s37
	s_add_i32 s44, s36, 0x12000
	s_lshl_b64 s[14:15], s[12:13], 11
	v_lshl_add_u32 v2, v2, 1, v3
	global_load_lds_dwordx4 v0, s[10:11]
	v_mov_b32_e32 v3, v1
	s_mov_b32 m0, s44
	s_add_u32 s22, s38, s14
	v_lshl_add_u64 v[4:5], s[10:11], 0, v[0:1]
	s_waitcnt vmcnt(1)
	v_lshl_add_u64 v[6:7], s[10:11], 0, v[2:3]
	global_load_lds_dwordx4 v2, s[10:11]
	s_addc_u32 s23, s39, s15
	s_or_b32 s10, s60, 0x80
	s_ashr_i32 s11, s10, 31
	s_add_i32 s45, s36, 0x2000
	s_lshl_b64 s[10:11], s[10:11], 11
	s_mov_b32 m0, s36
	s_add_u32 s10, s7, s10
	global_load_lds_dwordx4 v0, s[22:23]
	s_mov_b32 m0, s45
	s_addc_u32 s11, s16, s11
	s_add_i32 s57, s36, 0x14000
	global_load_lds_dwordx4 v2, s[22:23]
	s_mov_b32 m0, s57
	s_add_i32 s61, s36, 0x16000
	global_load_lds_dwordx4 v0, s[10:11]
	s_mov_b32 m0, s61
	v_lshl_add_u64 v[12:13], s[10:11], 0, v[0:1]
	v_lshl_add_u64 v[14:15], s[10:11], 0, v[2:3]
	global_load_lds_dwordx4 v2, s[10:11]
	s_or_b32 s10, s12, 0x80
	s_ashr_i32 s11, s10, 31
	s_lshl_b64 s[16:17], s[10:11], 11
	s_add_u32 s16, s38, s16
	s_addc_u32 s17, s39, s17
	s_add_i32 s70, s36, 0x4000
	s_mov_b32 m0, s70
	s_add_i32 s71, s36, 0x6000
	global_load_lds_dwordx4 v0, s[16:17]
	s_mov_b32 m0, s71
	v_ashrrev_i32_e32 v17, 8, v142
	global_load_lds_dwordx4 v2, s[16:17]
	v_lshl_add_u64 v[8:9], s[22:23], 0, v[0:1]
	v_lshl_add_u64 v[10:11], s[22:23], 0, v[2:3]
	v_cmp_eq_u32_e32 vcc, 1, v17
	s_and_saveexec_b64 s[42:43], vcc
	s_cbranch_execz .LBB0_1074
	s_barrier

.LBB0_1086:
	s_and_b64 vcc, exec, s[10:11]
	s_cbranch_vccz .LBB0_1142
	s_cmp_gt_i32 s49, 4
	s_mov_b64 s[10:11], -1
	s_cbranch_scc0 .LBB0_1127
	v_mov_b32_e32 v140, v201
	s_lshl_b32 s17, s30, 8
	v_ashrrev_i32_e32 v0, 31, v140
	v_lshrrev_b32_e32 v0, 26, v0
	v_add_u32_e32 v0, v140, v0
	v_ashrrev_i32_e32 v14, 6, v0
	v_bfe_i32 v0, v140, 27, 1
	v_lshlrev_b32_e32 v2, 4, v140
	v_lshrrev_b32_e32 v0, 22, v0
	v_add_u32_e32 v0, v2, v0
	v_and_b32_e32 v0, 0xfffffc00, v0
	v_sub_u32_e32 v0, v2, v0
	v_lshrrev_b32_e32 v3, 4, v0
	v_bitop3_b32 v3, v3, v0, 32 bitop3:0x6c
	v_ashrrev_i32_e32 v0, 31, v0
	v_lshrrev_b32_e32 v0, 26, v0
	v_lshlrev_b32_e32 v4, 3, v14
	v_add_u32_e32 v0, v3, v0
	v_and_b32_e32 v4, 0xfffff0, v4
	v_ashrrev_i32_e32 v16, 6, v0
	v_add_u32_e32 v0, v16, v4
	v_lshlrev_b32_e32 v4, 5, v14
	v_and_b32_e32 v15, 32, v4
	v_mul_i32_i24_e32 v4, 64, v16
	v_sub_u32_e32 v3, v3, v4
	v_ashrrev_i16_sdwa v3, v217, sext(v3) dst_sel:DWORD dst_unused:UNUSED_PAD src0_sel:DWORD src1_sel:BYTE_0
	v_add_u32_e32 v2, 0x2000, v2
	v_bfe_i32 v17, v3, 0, 16
	v_ashrrev_i32_e32 v3, 31, v2
	v_lshrrev_b32_e32 v3, 22, v3
	v_add_u32_e32 v3, v2, v3
	v_ashrrev_i32_e32 v20, 10, v3
	v_mul_i32_i24_e32 v3, 0x400, v20
	v_sub_u32_e32 v2, v2, v3
	v_lshrrev_b32_e32 v3, 4, v2
	v_bitop3_b32 v2, v3, v2, 32 bitop3:0x6c
	v_ashrrev_i32_e32 v4, 31, v2
	v_lshrrev_b32_e32 v4, 26, v4
	v_add_u32_e32 v4, v2, v4
	v_ashrrev_i32_e32 v19, 6, v140
	v_lshlrev_b32_e32 v3, 3, v20
	v_ashrrev_i32_e32 v22, 6, v4
	v_and_b32_e32 v4, 0xc0, v4
	v_readfirstlane_b32 s7, v19
	v_and_b32_e32 v3, 0xfffff0, v3
	v_sub_u32_e32 v2, v2, v4
	s_lshl_b32 s33, s7, 10
	s_movk_i32 s7, 0xb00
	v_add_u32_e32 v3, v22, v3
	v_ashrrev_i16_sdwa v2, v217, sext(v2) dst_sel:DWORD dst_unused:UNUSED_PAD src0_sel:DWORD src1_sel:BYTE_0
	v_mul_lo_u32 v0, v0, s7
	v_bfe_i32 v23, v2, 0, 16
	v_mul_lo_u32 v2, v3, s7
	s_lshl_b32 s7, s6, 8
	s_mul_i32 s44, s6, 0x160000
	v_readlane_b32 s16, v254, 53
	s_mul_hi_i32 s45, s7, 0x1600
	s_add_u32 s10, s16, s44
	v_readlane_b32 s20, v254, 55
	v_lshlrev_b32_e32 v5, 5, v20
	s_addc_u32 s11, s20, s45
	s_add_i32 s22, s33, 0
	v_or_b32_e32 v0, v0, v15
	v_and_b32_e32 v21, 32, v5
	s_add_i32 s23, s22, 0x10000
	v_add_lshl_u32 v0, v0, v17, 1
	v_or_b32_e32 v2, v2, v21
	s_mov_b32 m0, s23
	s_add_i32 s24, s22, 0x12000
	v_add_lshl_u32 v130, v2, v23, 1
	global_load_lds_dwordx4 v0, s[10:11]
	v_mov_b32_e32 v131, v1
	s_mov_b32 m0, s24
	s_mul_i32 s12, s30, 0x160000
	v_readlane_b32 s14, v255, 27
	v_lshl_add_u64 v[2:3], s[10:11], 0, v[0:1]
	v_lshl_add_u64 v[4:5], s[10:11], 0, v[130:131]
	global_load_lds_dwordx4 v130, s[10:11]
	s_mul_hi_i32 s13, s17, 0x1600
	v_readlane_b32 s15, v255, 28
	s_add_u32 s10, s14, s12
	s_addc_u32 s11, s15, s13
	s_mov_b32 m0, s22
	s_add_i32 s25, s22, 0x2000
	global_load_lds_dwordx4 v0, s[10:11]
	s_mov_b32 m0, s25
	s_waitcnt vmcnt(3)
	v_lshl_add_u64 v[6:7], s[10:11], 0, v[0:1]
	v_lshl_add_u64 v[8:9], s[10:11], 0, v[130:131]
	global_load_lds_dwordx4 v130, s[10:11]
	s_or_b32 s10, s7, 0x80
	s_mul_hi_i32 s11, s10, 0x1600
	s_mulk_i32 s10, 0x1600
	s_add_u32 s10, s16, s10
	s_addc_u32 s11, s20, s11
	s_add_i32 s36, s22, 0x14000
	s_mov_b32 m0, s36
	s_add_i32 s37, s22, 0x16000
	global_load_lds_dwordx4 v0, s[10:11]
	s_mov_b32 m0, s37
	s_or_b32 s16, s17, 0x80
	v_lshl_add_u64 v[10:11], s[10:11], 0, v[0:1]
	v_lshl_add_u64 v[12:13], s[10:11], 0, v[130:131]
	global_load_lds_dwordx4 v130, s[10:11]
	s_mul_i32 s10, s16, 0x1600
	s_mul_hi_i32 s11, s16, 0x1600
	s_add_u32 s10, s14, s10
	s_addc_u32 s11, s15, s11
	s_add_i32 s42, s22, 0x4000
	s_mov_b32 m0, s42
	s_add_i32 s43, s22, 0x6000
	global_load_lds_dwordx4 v0, s[10:11]
	s_mov_b32 m0, s43
	v_ashrrev_i32_e32 v18, 8, v140
	global_load_lds_dwordx4 v130, s[10:11]
	v_cmp_eq_u32_e32 vcc, 1, v18
	s_and_saveexec_b64 s[14:15], vcc
	s_cbranch_execz .LBB0_1090
	s_barrier

.LBB0_1127:
	s_and_b64 vcc, exec, s[10:11]
	s_cbranch_vccz .LBB0_1141
	v_mov_b32_e32 v142, v201
	s_lshl_b32 s60, s6, 9
	v_ashrrev_i32_e32 v0, 31, v142
	v_lshrrev_b32_e32 v0, 26, v0
	v_add_u32_e32 v0, v142, v0
	v_ashrrev_i32_e32 v16, 6, v0
	v_bfe_i32 v0, v142, 27, 1
	v_lshlrev_b32_e32 v2, 4, v142
	v_lshrrev_b32_e32 v0, 22, v0
	v_add_u32_e32 v0, v2, v0
	v_and_b32_e32 v0, 0xfffffc00, v0
	v_sub_u32_e32 v0, v2, v0
	v_lshrrev_b32_e32 v3, 4, v0
	v_bitop3_b32 v3, v3, v0, 32 bitop3:0x6c
	v_ashrrev_i32_e32 v0, 31, v0
	v_lshrrev_b32_e32 v0, 26, v0
	v_add_u32_e32 v0, v3, v0
	v_ashrrev_i32_e32 v18, 6, v0
	v_mul_i32_i24_e32 v5, 64, v18
	v_sub_u32_e32 v3, v3, v5
	v_lshlrev_b32_e32 v4, 3, v16
	v_lshlrev_b32_e32 v0, 5, v16
	v_ashrrev_i16_sdwa v3, v217, sext(v3) dst_sel:DWORD dst_unused:UNUSED_PAD src0_sel:DWORD src1_sel:BYTE_0
	v_and_b32_e32 v4, 0x1ffff0, v4
	v_and_b32_e32 v0, 32, v0
	v_bfe_i32 v19, v3, 0, 16
	v_add_u32_e32 v0, v0, v19
	v_add_lshl_u32 v3, v18, v4, 11
	v_add_u32_e32 v2, 0x2000, v2
	v_lshl_add_u32 v0, v0, 1, v3
	v_ashrrev_i32_e32 v3, 31, v2
	v_lshrrev_b32_e32 v3, 22, v3
	v_add_u32_e32 v3, v2, v3
	v_ashrrev_i32_e32 v21, 10, v3
	v_mul_i32_i24_e32 v3, 0x400, v21
	v_sub_u32_e32 v2, v2, v3
	v_lshrrev_b32_e32 v3, 4, v2
	v_bitop3_b32 v2, v3, v2, 32 bitop3:0x6c
	v_ashrrev_i32_e32 v4, 31, v2
	v_ashrrev_i32_e32 v20, 6, v142
	v_lshrrev_b32_e32 v4, 26, v4
	v_readfirstlane_b32 s7, v20
	v_add_u32_e32 v4, v2, v4
	s_ashr_i32 s61, s60, 31
	s_lshl_b32 s33, s7, 10
	v_ashrrev_i32_e32 v22, 6, v4
	v_and_b32_e32 v4, 0xc0, v4
	s_lshl_b32 s12, s30, 8
	s_lshl_b64 s[24:25], s[60:61], 11
	v_readlane_b32 s7, v255, 16
	v_sub_u32_e32 v2, v2, v4
	s_add_u32 s10, s7, s24
	v_readlane_b32 s16, v255, 25
	v_lshlrev_b32_e32 v3, 3, v21
	v_lshlrev_b32_e32 v5, 5, v21
	v_ashrrev_i16_sdwa v2, v217, sext(v2) dst_sel:DWORD dst_unused:UNUSED_PAD src0_sel:DWORD src1_sel:BYTE_0
	s_addc_u32 s11, s16, s25
	s_add_i32 s36, s33, 0
	v_and_b32_e32 v3, 0x1ffff0, v3
	v_and_b32_e32 v5, 32, v5
	v_bfe_i32 v23, v2, 0, 16
	s_add_i32 s37, s36, 0x10000
	s_ashr_i32 s13, s12, 31
	v_add_u32_e32 v2, v5, v23
	v_add_lshl_u32 v3, v22, v3, 11
	s_mov_b32 m0, s37
	s_add_i32 s44, s36, 0x12000
	s_lshl_b64 s[14:15], s[12:13], 11
	v_lshl_add_u32 v2, v2, 1, v3
	global_load_lds_dwordx4 v0, s[10:11]
	v_mov_b32_e32 v3, v1
	s_mov_b32 m0, s44
	s_add_u32 s22, s38, s14
	v_lshl_add_u64 v[4:5], s[10:11], 0, v[0:1]
	s_waitcnt vmcnt(1)
	v_lshl_add_u64 v[6:7], s[10:11], 0, v[2:3]
	global_load_lds_dwordx4 v2, s[10:11]
	s_addc_u32 s23, s39, s15
	s_or_b32 s10, s60, 0x80
	s_ashr_i32 s11, s10, 31
	s_add_i32 s45, s36, 0x2000
	s_lshl_b64 s[10:11], s[10:11], 11
	s_mov_b32 m0, s36
	s_add_u32 s10, s7, s10
	global_load_lds_dwordx4 v0, s[22:23]
	s_mov_b32 m0, s45
	s_addc_u32 s11, s16, s11
	s_add_i32 s57, s36, 0x14000
	global_load_lds_dwordx4 v2, s[22:23]
	s_mov_b32 m0, s57
	s_add_i32 s61, s36, 0x16000
	global_load_lds_dwordx4 v0, s[10:11]
	s_mov_b32 m0, s61
	v_lshl_add_u64 v[12:13], s[10:11], 0, v[0:1]
	v_lshl_add_u64 v[14:15], s[10:11], 0, v[2:3]
	global_load_lds_dwordx4 v2, s[10:11]
	s_or_b32 s10, s12, 0x80
	s_ashr_i32 s11, s10, 31
	s_lshl_b64 s[16:17], s[10:11], 11
	s_add_u32 s16, s38, s16
	s_addc_u32 s17, s39, s17
	s_add_i32 s70, s36, 0x4000
	s_mov_b32 m0, s70
	s_add_i32 s71, s36, 0x6000
	global_load_lds_dwordx4 v0, s[16:17]
	s_mov_b32 m0, s71
	v_ashrrev_i32_e32 v17, 8, v142
	global_load_lds_dwordx4 v2, s[16:17]
	v_lshl_add_u64 v[8:9], s[22:23], 0, v[0:1]
	v_lshl_add_u64 v[10:11], s[22:23], 0, v[2:3]
	v_cmp_eq_u32_e32 vcc, 1, v17
	s_and_saveexec_b64 s[42:43], vcc
	s_cbranch_execz .LBB0_1130
	s_barrier

.LBB0_1143:
	s_and_b64 vcc, exec, s[10:11]
	s_cbranch_vccz .LBB0_1277
	s_cmp_gt_i32 s49, 1
	s_mov_b64 s[10:11], -1
	s_cbranch_scc0 .LBB0_1266
	s_cmp_gt_i32 s49, 2
	s_mov_b64 s[8:9], -1
	s_cbranch_scc0 .LBB0_1185
	v_mov_b32_e32 v142, v201
	s_lshl_b32 s12, s6, 8
	v_ashrrev_i32_e32 v0, 31, v142
	v_lshrrev_b32_e32 v0, 26, v0
	v_add_u32_e32 v0, v142, v0
	v_ashrrev_i32_e32 v16, 6, v0
	v_bfe_i32 v0, v142, 27, 1
	v_lshlrev_b32_e32 v2, 4, v142
	v_lshrrev_b32_e32 v0, 22, v0
	v_add_u32_e32 v0, v2, v0
	v_and_b32_e32 v0, 0xfffffc00, v0
	v_sub_u32_e32 v0, v2, v0
	v_lshrrev_b32_e32 v3, 4, v0
	v_bitop3_b32 v3, v3, v0, 32 bitop3:0x6c
	v_ashrrev_i32_e32 v0, 31, v0
	v_lshrrev_b32_e32 v0, 26, v0
	v_lshlrev_b32_e32 v4, 3, v16
	v_add_u32_e32 v0, v3, v0
	v_and_b32_e32 v4, 0x1ffff0, v4
	v_ashrrev_i32_e32 v17, 6, v0
	v_add_u32_e32 v0, v17, v4
	v_lshlrev_b32_e32 v4, 5, v16
	v_and_b32_e32 v19, 32, v4
	v_mul_i32_i24_e32 v4, 64, v17
	v_sub_u32_e32 v3, v3, v4
	v_ashrrev_i16_sdwa v3, v217, sext(v3) dst_sel:DWORD dst_unused:UNUSED_PAD src0_sel:DWORD src1_sel:BYTE_0
	v_add_u32_e32 v2, 0x2000, v2
	v_bfe_i32 v20, v3, 0, 16
	v_ashrrev_i32_e32 v3, 31, v2
	v_lshrrev_b32_e32 v3, 22, v3
	v_add_u32_e32 v3, v2, v3
	v_ashrrev_i32_e32 v22, 10, v3
	v_mul_i32_i24_e32 v3, 0x400, v22
	v_sub_u32_e32 v2, v2, v3
	v_lshrrev_b32_e32 v3, 4, v2
	v_bitop3_b32 v2, v3, v2, 32 bitop3:0x6c
	v_ashrrev_i32_e32 v21, 6, v142
	v_ashrrev_i32_e32 v4, 31, v2
	v_readfirstlane_b32 s7, v21
	v_lshrrev_b32_e32 v4, 26, v4
	s_ashr_i32 s13, s12, 31
	s_lshl_b32 s33, s7, 10
	v_add_u32_e32 v4, v2, v4
	s_lshl_b32 s10, s30, 8
	s_lshl_b64 s[14:15], s[12:13], 11
	v_readlane_b32 s22, v254, 57
	v_lshlrev_b32_e32 v3, 3, v22
	v_ashrrev_i32_e32 v23, 6, v4
	v_and_b32_e32 v4, 0xc0, v4
	s_add_u32 s8, s22, s14
	v_readlane_b32 s23, v255, 1
	v_and_b32_e32 v3, 0x1ffff0, v3
	v_lshlrev_b32_e32 v5, 5, v22
	v_sub_u32_e32 v2, v2, v4
	s_addc_u32 s9, s23, s15
	s_add_i32 s7, s33, 0
	v_lshl_or_b32 v0, v0, 10, v19
	v_add_u32_e32 v3, v23, v3
	v_and_b32_e32 v24, 32, v5
	v_ashrrev_i16_sdwa v2, v217, sext(v2) dst_sel:DWORD dst_unused:UNUSED_PAD src0_sel:DWORD src1_sel:BYTE_0
	s_add_i32 s13, s7, 0x10000
	v_add_lshl_u32 v0, v0, v20, 1
	v_bfe_i32 v25, v2, 0, 16
	v_lshl_or_b32 v2, v3, 10, v24
	s_mov_b32 m0, s13
	s_add_i32 s36, s7, 0x12000
	s_ashr_i32 s11, s10, 31
	v_add_lshl_u32 v2, v2, v25, 1
	global_load_lds_dwordx4 v0, s[8:9]
	v_mov_b32_e32 v3, v1
	s_mov_b32 m0, s36
	s_lshl_b64 s[16:17], s[10:11], 11
	v_readlane_b32 s20, v255, 26
	v_lshl_add_u64 v[4:5], s[8:9], 0, v[0:1]
	s_waitcnt vmcnt(1)
	v_lshl_add_u64 v[6:7], s[8:9], 0, v[2:3]
	global_load_lds_dwordx4 v2, s[8:9]
	s_add_u32 s8, s20, s16
	v_readlane_b32 s21, v255, 3
	s_addc_u32 s9, s21, s17
	s_mov_b32 m0, s7
	s_add_i32 s11, s7, 0x2000
	global_load_lds_dwordx4 v0, s[8:9]
	s_mov_b32 m0, s11
	v_lshl_add_u64 v[8:9], s[8:9], 0, v[0:1]
	v_lshl_add_u64 v[10:11], s[8:9], 0, v[2:3]
	global_load_lds_dwordx4 v2, s[8:9]
	s_or_b32 s8, s12, 0x80
	s_ashr_i32 s9, s8, 31
	s_lshl_b64 s[8:9], s[8:9], 11
	s_add_u32 s8, s22, s8
	s_addc_u32 s9, s23, s9
	s_add_i32 s37, s7, 0x14000
	s_mov_b32 m0, s37
	s_add_i32 s42, s7, 0x16000
	global_load_lds_dwordx4 v0, s[8:9]
	s_mov_b32 m0, s42
	v_lshl_add_u64 v[12:13], s[8:9], 0, v[0:1]
	v_lshl_add_u64 v[14:15], s[8:9], 0, v[2:3]
	global_load_lds_dwordx4 v2, s[8:9]
	s_or_b32 s8, s10, 0x80
	s_ashr_i32 s9, s8, 31
	s_lshl_b64 s[22:23], s[8:9], 11
	s_add_u32 s22, s20, s22
	s_addc_u32 s23, s21, s23
	s_add_i32 s9, s7, 0x4000
	s_mov_b32 m0, s9
	s_add_i32 s43, s7, 0x6000
	global_load_lds_dwordx4 v0, s[22:23]
	s_mov_b32 m0, s43
	v_ashrrev_i32_e32 v18, 8, v142
	global_load_lds_dwordx4 v2, s[22:23]
	v_cmp_eq_u32_e32 vcc, 1, v18
	s_and_saveexec_b64 s[24:25], vcc
	s_cbranch_execz .LBB0_1148
	s_barrier

.LBB0_1266:
	s_mov_b64 s[8:9], 0
	s_and_b64 vcc, exec, s[10:11]
	s_cbranch_vccz .LBB0_1277
	s_cmp_gt_i32 s49, 0
	s_mov_b64 s[10:11], -1
	s_cbranch_scc0 .LBB0_1275
	v_mov_b32_e32 v142, v201
	s_lshl_b32 s12, s6, 8
	v_ashrrev_i32_e32 v0, 31, v142
	v_lshrrev_b32_e32 v0, 26, v0
	v_add_u32_e32 v0, v142, v0
	v_ashrrev_i32_e32 v16, 6, v0
	v_bfe_i32 v0, v142, 27, 1
	v_lshlrev_b32_e32 v2, 4, v142
	v_lshrrev_b32_e32 v0, 22, v0
	v_add_u32_e32 v0, v2, v0
	v_and_b32_e32 v0, 0xfffffc00, v0
	v_sub_u32_e32 v0, v2, v0
	v_lshrrev_b32_e32 v3, 4, v0
	v_bitop3_b32 v3, v3, v0, 32 bitop3:0x6c
	v_ashrrev_i32_e32 v0, 31, v0
	v_lshrrev_b32_e32 v0, 26, v0
	v_add_u32_e32 v0, v3, v0
	v_ashrrev_i32_e32 v18, 6, v0
	v_mul_i32_i24_e32 v5, 64, v18
	v_sub_u32_e32 v3, v3, v5
	v_lshlrev_b32_e32 v4, 3, v16
	v_lshlrev_b32_e32 v0, 5, v16
	v_ashrrev_i16_sdwa v3, v217, sext(v3) dst_sel:DWORD dst_unused:UNUSED_PAD src0_sel:DWORD src1_sel:BYTE_0
	v_and_b32_e32 v4, 0x1ffff0, v4
	v_and_b32_e32 v0, 32, v0
	v_bfe_i32 v19, v3, 0, 16
	v_add_u32_e32 v0, v0, v19
	v_add_lshl_u32 v3, v18, v4, 11
	v_add_u32_e32 v2, 0x2000, v2
	v_lshl_add_u32 v0, v0, 1, v3
	v_ashrrev_i32_e32 v3, 31, v2
	v_lshrrev_b32_e32 v3, 22, v3
	v_add_u32_e32 v3, v2, v3
	v_ashrrev_i32_e32 v21, 10, v3
	v_mul_i32_i24_e32 v3, 0x400, v21
	v_sub_u32_e32 v2, v2, v3
	v_lshrrev_b32_e32 v3, 4, v2
	v_bitop3_b32 v2, v3, v2, 32 bitop3:0x6c
	v_ashrrev_i32_e32 v4, 31, v2
	v_ashrrev_i32_e32 v20, 6, v142
	v_lshrrev_b32_e32 v4, 26, v4
	v_readfirstlane_b32 s7, v20
	v_add_u32_e32 v4, v2, v4
	s_ashr_i32 s13, s12, 31
	s_lshl_b32 s33, s7, 10
	v_ashrrev_i32_e32 v22, 6, v4
	v_and_b32_e32 v4, 0xc0, v4
	s_lshl_b32 s10, s30, 8
	s_lshl_b64 s[14:15], s[12:13], 11
	v_readlane_b32 s20, v255, 2
	v_sub_u32_e32 v2, v2, v4
	s_add_u32 s8, s20, s14
	v_readlane_b32 s21, v255, 5
	v_lshlrev_b32_e32 v3, 3, v21
	v_lshlrev_b32_e32 v5, 5, v21
	v_ashrrev_i16_sdwa v2, v217, sext(v2) dst_sel:DWORD dst_unused:UNUSED_PAD src0_sel:DWORD src1_sel:BYTE_0
	s_addc_u32 s9, s21, s15
	s_add_i32 s7, s33, 0
	v_and_b32_e32 v3, 0x1ffff0, v3
	v_and_b32_e32 v5, 32, v5
	v_bfe_i32 v23, v2, 0, 16
	s_add_i32 s13, s7, 0x10000
	v_add_u32_e32 v2, v5, v23
	v_add_lshl_u32 v3, v22, v3, 11
	s_mov_b32 m0, s13
	s_add_i32 s36, s7, 0x12000
	s_ashr_i32 s11, s10, 31
	v_lshl_add_u32 v2, v2, 1, v3
	global_load_lds_dwordx4 v0, s[8:9]
	v_mov_b32_e32 v3, v1
	s_mov_b32 m0, s36
	s_lshl_b64 s[16:17], s[10:11], 11
	v_lshl_add_u64 v[4:5], s[8:9], 0, v[0:1]
	s_waitcnt vmcnt(1)
	v_lshl_add_u64 v[6:7], s[8:9], 0, v[2:3]
	global_load_lds_dwordx4 v2, s[8:9]
	s_add_u32 s8, s38, s16
	s_addc_u32 s9, s39, s17
	s_mov_b32 m0, s7
	s_add_i32 s11, s7, 0x2000
	global_load_lds_dwordx4 v0, s[8:9]
	s_mov_b32 m0, s11
	v_lshl_add_u64 v[8:9], s[8:9], 0, v[0:1]
	v_lshl_add_u64 v[10:11], s[8:9], 0, v[2:3]
	global_load_lds_dwordx4 v2, s[8:9]
	s_or_b32 s8, s12, 0x80
	s_ashr_i32 s9, s8, 31
	s_lshl_b64 s[8:9], s[8:9], 11
	s_add_u32 s8, s20, s8
	s_addc_u32 s9, s21, s9
	s_add_i32 s37, s7, 0x14000
	s_mov_b32 m0, s37
	s_add_i32 s42, s7, 0x16000
	global_load_lds_dwordx4 v0, s[8:9]
	s_mov_b32 m0, s42
	v_lshl_add_u64 v[12:13], s[8:9], 0, v[0:1]
	v_lshl_add_u64 v[14:15], s[8:9], 0, v[2:3]
	global_load_lds_dwordx4 v2, s[8:9]
	s_or_b32 s8, s10, 0x80
	s_ashr_i32 s9, s8, 31
	s_lshl_b64 s[22:23], s[8:9], 11
	s_add_u32 s22, s38, s22
	s_addc_u32 s23, s39, s23
	s_add_i32 s9, s7, 0x4000
	s_mov_b32 m0, s9
	s_add_i32 s43, s7, 0x6000
	global_load_lds_dwordx4 v0, s[22:23]
	s_mov_b32 m0, s43
	v_ashrrev_i32_e32 v17, 8, v142
	global_load_lds_dwordx4 v2, s[22:23]
	v_cmp_eq_u32_e32 vcc, 1, v17
	s_and_saveexec_b64 s[24:25], vcc
	s_cbranch_execz .LBB0_1270
	s_barrier

.LBB0_1296:
	v_mov_b32_e32 v142, v201
	s_lshl_b32 s12, s6, 8
	v_ashrrev_i32_e32 v0, 31, v142
	v_lshrrev_b32_e32 v0, 26, v0
	v_add_u32_e32 v0, v142, v0
	v_ashrrev_i32_e32 v16, 6, v0
	v_bfe_i32 v0, v142, 27, 1
	v_lshlrev_b32_e32 v2, 4, v142
	v_lshrrev_b32_e32 v0, 22, v0
	v_add_u32_e32 v0, v2, v0
	v_and_b32_e32 v0, 0xfffffc00, v0
	v_sub_u32_e32 v0, v2, v0
	v_lshrrev_b32_e32 v3, 4, v0
	v_bitop3_b32 v3, v3, v0, 32 bitop3:0x6c
	v_ashrrev_i32_e32 v0, 31, v0
	v_lshrrev_b32_e32 v0, 26, v0
	v_add_u32_e32 v0, v3, v0
	v_ashrrev_i32_e32 v18, 6, v0
	v_mul_i32_i24_e32 v5, 64, v18
	v_sub_u32_e32 v3, v3, v5
	v_lshlrev_b32_e32 v4, 3, v16
	v_lshlrev_b32_e32 v0, 5, v16
	v_ashrrev_i16_sdwa v3, v217, sext(v3) dst_sel:DWORD dst_unused:UNUSED_PAD src0_sel:DWORD src1_sel:BYTE_0
	v_and_b32_e32 v4, 0x1ffff0, v4
	v_and_b32_e32 v0, 32, v0
	v_bfe_i32 v19, v3, 0, 16
	v_add_u32_e32 v0, v0, v19
	v_add_lshl_u32 v3, v18, v4, 11
	v_add_u32_e32 v2, 0x2000, v2
	v_lshl_add_u32 v0, v0, 1, v3
	v_ashrrev_i32_e32 v3, 31, v2
	v_lshrrev_b32_e32 v3, 22, v3
	v_add_u32_e32 v3, v2, v3
	v_ashrrev_i32_e32 v21, 10, v3
	v_mul_i32_i24_e32 v3, 0x400, v21
	v_sub_u32_e32 v2, v2, v3
	v_lshrrev_b32_e32 v3, 4, v2
	v_bitop3_b32 v2, v3, v2, 32 bitop3:0x6c
	v_ashrrev_i32_e32 v4, 31, v2
	v_ashrrev_i32_e32 v20, 6, v142
	v_lshrrev_b32_e32 v4, 26, v4
	v_readfirstlane_b32 s7, v20
	v_add_u32_e32 v4, v2, v4
	s_ashr_i32 s13, s12, 31
	s_lshl_b32 s33, s7, 10
	v_ashrrev_i32_e32 v22, 6, v4
	v_and_b32_e32 v4, 0xc0, v4
	s_lshl_b32 s10, s30, 8
	s_lshl_b64 s[14:15], s[12:13], 11
	v_readlane_b32 s20, v254, 62
	v_sub_u32_e32 v2, v2, v4
	s_add_u32 s8, s20, s14
	v_readlane_b32 s21, v255, 10
	v_lshlrev_b32_e32 v3, 3, v21
	v_lshlrev_b32_e32 v5, 5, v21
	v_ashrrev_i16_sdwa v2, v217, sext(v2) dst_sel:DWORD dst_unused:UNUSED_PAD src0_sel:DWORD src1_sel:BYTE_0
	s_addc_u32 s9, s21, s15
	s_add_i32 s7, s33, 0
	v_and_b32_e32 v3, 0x1ffff0, v3
	v_and_b32_e32 v5, 32, v5
	v_bfe_i32 v23, v2, 0, 16
	s_add_i32 s13, s7, 0x10000
	v_add_u32_e32 v2, v5, v23
	v_add_lshl_u32 v3, v22, v3, 11
	s_mov_b32 m0, s13
	s_add_i32 s28, s7, 0x12000
	s_ashr_i32 s11, s10, 31
	v_lshl_add_u32 v2, v2, 1, v3
	global_load_lds_dwordx4 v0, s[8:9]
	v_mov_b32_e32 v3, v1
	s_mov_b32 m0, s28
	s_lshl_b64 s[16:17], s[10:11], 11
	v_lshl_add_u64 v[4:5], s[8:9], 0, v[0:1]
	s_waitcnt vmcnt(1)
	v_lshl_add_u64 v[6:7], s[8:9], 0, v[2:3]
	global_load_lds_dwordx4 v2, s[8:9]
	s_add_u32 s8, s38, s16
	s_addc_u32 s9, s39, s17
	s_mov_b32 m0, s7
	s_add_i32 s11, s7, 0x2000
	global_load_lds_dwordx4 v0, s[8:9]
	s_mov_b32 m0, s11
	v_lshl_add_u64 v[8:9], s[8:9], 0, v[0:1]
	v_lshl_add_u64 v[10:11], s[8:9], 0, v[2:3]
	global_load_lds_dwordx4 v2, s[8:9]
	s_or_b32 s8, s12, 0x80
	s_ashr_i32 s9, s8, 31
	s_lshl_b64 s[8:9], s[8:9], 11
	s_add_u32 s8, s20, s8
	s_addc_u32 s9, s21, s9
	s_add_i32 s29, s7, 0x14000
	s_mov_b32 m0, s29
	s_add_i32 s36, s7, 0x16000
	global_load_lds_dwordx4 v0, s[8:9]
	s_mov_b32 m0, s36
	v_lshl_add_u64 v[12:13], s[8:9], 0, v[0:1]
	v_lshl_add_u64 v[14:15], s[8:9], 0, v[2:3]
	global_load_lds_dwordx4 v2, s[8:9]
	s_or_b32 s8, s10, 0x80
	s_ashr_i32 s9, s8, 31
	s_lshl_b64 s[22:23], s[8:9], 11
	s_add_u32 s22, s38, s22
	s_addc_u32 s23, s39, s23
	s_add_i32 s9, s7, 0x4000
	s_mov_b32 m0, s9
	s_add_i32 s37, s7, 0x6000
	global_load_lds_dwordx4 v0, s[22:23]
	s_mov_b32 m0, s37
	v_ashrrev_i32_e32 v17, 8, v142
	global_load_lds_dwordx4 v2, s[22:23]
	v_cmp_eq_u32_e32 vcc, 1, v17
	s_and_saveexec_b64 s[24:25], vcc
	s_cbranch_execz .LBB0_1298
	s_barrier

.LBB0_1303:
	v_mov_b32_e32 v142, v201
	s_lshl_b32 s15, s30, 8
	v_ashrrev_i32_e32 v0, 31, v142
	v_lshrrev_b32_e32 v0, 26, v0
	v_add_u32_e32 v0, v142, v0
	v_ashrrev_i32_e32 v16, 6, v0
	v_bfe_i32 v0, v142, 27, 1
	v_lshlrev_b32_e32 v2, 4, v142
	v_lshrrev_b32_e32 v0, 22, v0
	v_add_u32_e32 v0, v2, v0
	v_and_b32_e32 v0, 0xfffffc00, v0
	v_sub_u32_e32 v0, v2, v0
	v_lshrrev_b32_e32 v3, 4, v0
	v_bitop3_b32 v3, v3, v0, 32 bitop3:0x6c
	v_ashrrev_i32_e32 v0, 31, v0
	v_lshrrev_b32_e32 v0, 26, v0
	v_lshlrev_b32_e32 v4, 3, v16
	v_add_u32_e32 v0, v3, v0
	v_and_b32_e32 v4, 0x7ffff0, v4
	v_ashrrev_i32_e32 v17, 6, v0
	v_add_u32_e32 v0, v17, v4
	v_lshlrev_b32_e32 v4, 5, v16
	v_and_b32_e32 v18, 32, v4
	v_mul_i32_i24_e32 v4, 64, v17
	v_sub_u32_e32 v3, v3, v4
	v_ashrrev_i16_sdwa v3, v217, sext(v3) dst_sel:DWORD dst_unused:UNUSED_PAD src0_sel:DWORD src1_sel:BYTE_0
	v_add_u32_e32 v2, 0x2000, v2
	v_bfe_i32 v20, v3, 0, 16
	v_ashrrev_i32_e32 v3, 31, v2
	v_lshrrev_b32_e32 v3, 22, v3
	v_add_u32_e32 v3, v2, v3
	v_ashrrev_i32_e32 v22, 10, v3
	v_mul_i32_i24_e32 v3, 0x400, v22
	v_sub_u32_e32 v2, v2, v3
	v_lshrrev_b32_e32 v3, 4, v2
	v_bitop3_b32 v2, v3, v2, 32 bitop3:0x6c
	v_ashrrev_i32_e32 v4, 31, v2
	v_lshrrev_b32_e32 v4, 26, v4
	v_add_u32_e32 v4, v2, v4
	v_ashrrev_i32_e32 v21, 6, v142
	v_lshlrev_b32_e32 v3, 3, v22
	v_ashrrev_i32_e32 v23, 6, v4
	v_and_b32_e32 v4, 0xc0, v4
	v_readfirstlane_b32 s7, v21
	v_and_b32_e32 v3, 0x7ffff0, v3
	v_sub_u32_e32 v2, v2, v4
	s_lshl_b32 s33, s7, 10
	s_movk_i32 s7, 0x600
	v_add_u32_e32 v3, v23, v3
	v_ashrrev_i16_sdwa v2, v217, sext(v2) dst_sel:DWORD dst_unused:UNUSED_PAD src0_sel:DWORD src1_sel:BYTE_0
	v_mul_lo_u32 v0, v0, s7
	v_bfe_i32 v25, v2, 0, 16
	v_mul_lo_u32 v2, v3, s7
	s_lshl_b32 s7, s6, 8
	s_mul_i32 s36, s6, 0xc0000
	v_readlane_b32 s14, v254, 59
	s_mul_hi_i32 s37, s7, 0xc00
	s_add_u32 s8, s14, s36
	v_readlane_b32 s20, v254, 61
	v_lshlrev_b32_e32 v5, 5, v22
	s_addc_u32 s9, s20, s37
	s_add_i32 s16, s33, 0
	v_or_b32_e32 v0, v0, v18
	v_and_b32_e32 v24, 32, v5
	s_add_i32 s17, s16, 0x10000
	v_add_lshl_u32 v0, v0, v20, 1
	v_or_b32_e32 v2, v2, v24
	s_mov_b32 m0, s17
	s_add_i32 s22, s16, 0x12000
	v_add_lshl_u32 v2, v2, v25, 1
	global_load_lds_dwordx4 v0, s[8:9]
	v_mov_b32_e32 v3, v1
	s_mov_b32 m0, s22
	v_lshl_add_u64 v[4:5], s[8:9], 0, v[0:1]
	s_waitcnt vmcnt(1)
	v_lshl_add_u64 v[6:7], s[8:9], 0, v[2:3]
	global_load_lds_dwordx4 v2, s[8:9]
	s_mul_i32 s8, s30, 0xc0000
	v_readlane_b32 s12, v253, 62
	s_mul_hi_i32 s9, s15, 0xc00
	v_readlane_b32 s13, v253, 63
	s_add_u32 s10, s12, s8
	s_addc_u32 s11, s13, s9
	s_mov_b32 m0, s16
	s_add_i32 s23, s16, 0x2000
	global_load_lds_dwordx4 v0, s[10:11]
	s_mov_b32 m0, s23
	v_lshl_add_u64 v[8:9], s[10:11], 0, v[0:1]
	v_lshl_add_u64 v[10:11], s[10:11], 0, v[2:3]
	global_load_lds_dwordx4 v2, s[10:11]
	s_or_b32 s10, s7, 0x80
	s_mul_hi_i32 s11, s10, 0xc00
	s_mulk_i32 s10, 0xc00
	s_add_u32 s10, s14, s10
	s_addc_u32 s11, s20, s11
	s_add_i32 s24, s16, 0x14000
	s_mov_b32 m0, s24
	s_add_i32 s25, s16, 0x16000
	global_load_lds_dwordx4 v0, s[10:11]
	s_mov_b32 m0, s25
	s_or_b32 s14, s15, 0x80
	v_lshl_add_u64 v[12:13], s[10:11], 0, v[0:1]
	v_lshl_add_u64 v[14:15], s[10:11], 0, v[2:3]
	global_load_lds_dwordx4 v2, s[10:11]
	s_mul_i32 s10, s14, 0xc00
	s_mul_hi_i32 s11, s14, 0xc00
	s_add_u32 s10, s12, s10
	s_addc_u32 s11, s13, s11
	s_add_i32 s28, s16, 0x4000
	s_mov_b32 m0, s28
	s_add_i32 s29, s16, 0x6000
	global_load_lds_dwordx4 v0, s[10:11]
	s_mov_b32 m0, s29
	v_ashrrev_i32_e32 v19, 8, v142
	global_load_lds_dwordx4 v2, s[10:11]
	v_cmp_eq_u32_e32 vcc, 1, v19
	s_and_saveexec_b64 s[12:13], vcc
	s_cbranch_execz .LBB0_1305
	s_barrier
